# pool job: matvec weights prefetched 8 iterations ahead + 16 LDS reads per iteration batched; window-mean stage LDS reads batched per token (same accumulation order)
# speedup vs baseline: 1.0240x; 1.0070x over previous
; __device__ __forceinline__ float bf2f(u16 h) { return __uint_as_float(((unsigned)h) << 16); }
; __device__ __forceinline__ void pool_job(const Params& p, char* smem, int l, int seqrow0, int L, int t0) {
;     ...
;     const int ch = tid, g = ch >> 6, wdt = 2 << g;
;     for (int tt = 0; tt < 32; ++tt) {
;       int t = t0 + tt;
;       int lo = t - wdt / 2, hi = lo + wdt;
;       lo = lo < 0 ? 0 : lo; hi = hi > L ? L : hi;
;       float s = 0.f;
;       for (int pp = lo; pp < hi; ++pp) s += bf2f(us[(pp - t0 + 8) * 256 + ch]);
;       float mean = s / (float)(hi - lo);
;       ds[tt * 256 + ch] = mean - bf2f(us[(tt + 8) * 256 + ch]);
;     }
.LBB0_823:
	v_readfirstlane_b32 s15, v3
	s_cmp_eq_u32 s15, 2
	s_cbranch_scc1 .Lpool_w2
	s_cmp_eq_u32 s15, 4
	s_cbranch_scc1 .Lpool_w4
	s_cmp_eq_u32 s15, 8
	s_cbranch_scc1 .Lpool_w8
	s_cmp_eq_u32 s15, 16
	s_cbranch_scc1 .Lpool_w16
	s_branch .Lpool_w16
.Lpool_w2:
	v_add_u32_e32 v9, s14, v4
	v_add_u32_e32 v11, v9, v3
	v_max_i32_e32 v10, 0, v9
	v_min_i32_e32 v11, s19, v11
	v_lshl_add_u32 v12, v10, 9, v6
	v_lshl_add_u32 v13, s14, 9, v5
	v_sub_u32_e32 v14, v11, v10
	ds_read_u16 v241, v12 offset:0
	ds_read_u16 v242, v12 offset:512
	ds_read_u16 v232, v13 offset:4096
	v_readfirstlane_b32 s4, v14
	v_mov_b32_e32 v9, 0
	s_waitcnt lgkmcnt(0)
	s_cmp_le_i32 s4, 0
	s_cbranch_scc1 .Lpool_w2_sum
	v_lshlrev_b32_e32 v15, 16, v241
	v_add_f32_e32 v9, v9, v15
	s_cmp_le_i32 s4, 1
	s_cbranch_scc1 .Lpool_w2_sum
	v_lshlrev_b32_e32 v15, 16, v242
	v_add_f32_e32 v9, v9, v15
.Lpool_w2_sum:
	v_cvt_f32_i32_e32 v10, v14
	s_nop 0
	v_div_scale_f32 v11, s[4:5], v10, v10, v9
	v_rcp_f32_e32 v12, v11
	s_nop 0
	v_fma_f32 v13, -v11, v12, 1.0
	v_fmac_f32_e32 v12, v13, v12
	v_div_scale_f32 v13, vcc, v9, v10, v9
	v_mul_f32_e32 v14, v13, v12
	v_fma_f32 v15, -v11, v14, v13
	v_fmac_f32_e32 v14, v15, v12
	v_fma_f32 v11, -v11, v14, v13
	s_nop 1
	v_div_fmas_f32 v11, v11, v12, v14
	v_div_fixup_f32 v9, v11, v10, v9
	v_lshlrev_b32_e32 v10, 16, v232
	v_sub_f32_e32 v9, v9, v10
	v_lshl_add_u32 v10, s14, 10, v0
	ds_write_b32 v10, v9 offset:24576
	s_add_i32 s14, s14, 1
	s_cmp_eq_u32 s14, 32
	s_cbranch_scc0 .Lpool_w2
	s_branch .LBB0_831
.Lpool_w4:
	v_add_u32_e32 v9, s14, v4
	v_add_u32_e32 v11, v9, v3
	v_max_i32_e32 v10, 0, v9
	v_min_i32_e32 v11, s19, v11
	v_lshl_add_u32 v12, v10, 9, v6
	v_lshl_add_u32 v13, s14, 9, v5
	v_sub_u32_e32 v14, v11, v10
	ds_read_u16 v241, v12 offset:0
	ds_read_u16 v242, v12 offset:512
	ds_read_u16 v243, v12 offset:1024
	ds_read_u16 v244, v12 offset:1536
	ds_read_u16 v232, v13 offset:4096
	v_readfirstlane_b32 s4, v14
	v_mov_b32_e32 v9, 0
	s_waitcnt lgkmcnt(0)
	s_cmp_le_i32 s4, 0
	s_cbranch_scc1 .Lpool_w4_sum
	v_lshlrev_b32_e32 v15, 16, v241
	v_add_f32_e32 v9, v9, v15
	s_cmp_le_i32 s4, 1
	s_cbranch_scc1 .Lpool_w4_sum
	v_lshlrev_b32_e32 v15, 16, v242
	v_add_f32_e32 v9, v9, v15
	s_cmp_le_i32 s4, 2
	s_cbranch_scc1 .Lpool_w4_sum
	v_lshlrev_b32_e32 v15, 16, v243
	v_add_f32_e32 v9, v9, v15
	s_cmp_le_i32 s4, 3
	s_cbranch_scc1 .Lpool_w4_sum
	v_lshlrev_b32_e32 v15, 16, v244
	v_add_f32_e32 v9, v9, v15

; __device__ __forceinline__ float bf2f(u16 h) { return __uint_as_float(((unsigned)h) << 16); }
; __device__ __forceinline__ void pool_job(const Params& p, char* smem, int l, int seqrow0, int L, int t0) {
;     ...
;     const int ch = tid, g = ch >> 6, wdt = 2 << g;
;     for (int tt = 0; tt < 32; ++tt) {
;       int t = t0 + tt;
;       int lo = t - wdt / 2, hi = lo + wdt;
;       lo = lo < 0 ? 0 : lo; hi = hi > L ? L : hi;
;       float s = 0.f;
;       for (int pp = lo; pp < hi; ++pp) s += bf2f(us[(pp - t0 + 8) * 256 + ch]);
;       float mean = s / (float)(hi - lo);
;       ds[tt * 256 + ch] = mean - bf2f(us[(tt + 8) * 256 + ch]);
;     }
.Lpool_w8:
	v_add_u32_e32 v9, s14, v4
	v_add_u32_e32 v11, v9, v3
	v_max_i32_e32 v10, 0, v9
	v_min_i32_e32 v11, s19, v11
	v_lshl_add_u32 v12, v10, 9, v6
	v_lshl_add_u32 v13, s14, 9, v5
	v_sub_u32_e32 v14, v11, v10
	ds_read_u16 v241, v12 offset:0
	ds_read_u16 v242, v12 offset:512
	ds_read_u16 v243, v12 offset:1024
	ds_read_u16 v244, v12 offset:1536
	ds_read_u16 v245, v12 offset:2048
	ds_read_u16 v246, v12 offset:2560
	ds_read_u16 v247, v12 offset:3072
	ds_read_u16 v248, v12 offset:3584
	ds_read_u16 v232, v13 offset:4096
	v_readfirstlane_b32 s4, v14
	v_mov_b32_e32 v9, 0
	s_waitcnt lgkmcnt(0)
	s_cmp_le_i32 s4, 0
	s_cbranch_scc1 .Lpool_w8_sum
	v_lshlrev_b32_e32 v15, 16, v241
	v_add_f32_e32 v9, v9, v15
	s_cmp_le_i32 s4, 1
	s_cbranch_scc1 .Lpool_w8_sum
	v_lshlrev_b32_e32 v15, 16, v242
	v_add_f32_e32 v9, v9, v15
	s_cmp_le_i32 s4, 2
	s_cbranch_scc1 .Lpool_w8_sum
	v_lshlrev_b32_e32 v15, 16, v243
	v_add_f32_e32 v9, v9, v15
	s_cmp_le_i32 s4, 3
	s_cbranch_scc1 .Lpool_w8_sum
	v_lshlrev_b32_e32 v15, 16, v244
	v_add_f32_e32 v9, v9, v15
	s_cmp_le_i32 s4, 4
	s_cbranch_scc1 .Lpool_w8_sum
	v_lshlrev_b32_e32 v15, 16, v245
	v_add_f32_e32 v9, v9, v15
	s_cmp_le_i32 s4, 5
	s_cbranch_scc1 .Lpool_w8_sum
	v_lshlrev_b32_e32 v15, 16, v246
	v_add_f32_e32 v9, v9, v15
	s_cmp_le_i32 s4, 6
	s_cbranch_scc1 .Lpool_w8_sum
	v_lshlrev_b32_e32 v15, 16, v247
	v_add_f32_e32 v9, v9, v15
	s_cmp_le_i32 s4, 7
	s_cbranch_scc1 .Lpool_w8_sum
	v_lshlrev_b32_e32 v15, 16, v248
	v_add_f32_e32 v9, v9, v15

; __device__ __forceinline__ float bf2f(u16 h) { return __uint_as_float(((unsigned)h) << 16); }
; __device__ __forceinline__ void pool_job(const Params& p, char* smem, int l, int seqrow0, int L, int t0) {
;     ...
;     const int ch = tid, g = ch >> 6, wdt = 2 << g;
;     for (int tt = 0; tt < 32; ++tt) {
;       int t = t0 + tt;
;       int lo = t - wdt / 2, hi = lo + wdt;
;       lo = lo < 0 ? 0 : lo; hi = hi > L ? L : hi;
;       float s = 0.f;
;       for (int pp = lo; pp < hi; ++pp) s += bf2f(us[(pp - t0 + 8) * 256 + ch]);
;       float mean = s / (float)(hi - lo);
;       ds[tt * 256 + ch] = mean - bf2f(us[(tt + 8) * 256 + ch]);
;     }
.Lpool_w16:
	v_add_u32_e32 v9, s14, v4
	v_add_u32_e32 v11, v9, v3
	v_max_i32_e32 v10, 0, v9
	v_min_i32_e32 v11, s19, v11
	v_lshl_add_u32 v12, v10, 9, v6
	v_lshl_add_u32 v13, s14, 9, v5
	v_sub_u32_e32 v14, v11, v10
	ds_read_u16 v241, v12 offset:0
	ds_read_u16 v242, v12 offset:512
	ds_read_u16 v243, v12 offset:1024
	ds_read_u16 v244, v12 offset:1536
	ds_read_u16 v245, v12 offset:2048
	ds_read_u16 v246, v12 offset:2560
	ds_read_u16 v247, v12 offset:3072
	ds_read_u16 v248, v12 offset:3584
	ds_read_u16 v249, v12 offset:4096
	ds_read_u16 v250, v12 offset:4608
	ds_read_u16 v251, v12 offset:5120
	ds_read_u16 v252, v12 offset:5632
	ds_read_u16 v253, v12 offset:6144
	ds_read_u16 v254, v12 offset:6656
	ds_read_u16 v255, v12 offset:7168
	ds_read_u16 v233, v12 offset:7680
	ds_read_u16 v232, v13 offset:4096
	v_readfirstlane_b32 s4, v14
	v_mov_b32_e32 v9, 0
	s_waitcnt lgkmcnt(0)
	s_cmp_le_i32 s4, 0
	s_cbranch_scc1 .Lpool_w16_sum
	v_lshlrev_b32_e32 v15, 16, v241
	v_add_f32_e32 v9, v9, v15
	s_cmp_le_i32 s4, 1
	s_cbranch_scc1 .Lpool_w16_sum
	v_lshlrev_b32_e32 v15, 16, v242
	v_add_f32_e32 v9, v9, v15
	s_cmp_le_i32 s4, 2
	s_cbranch_scc1 .Lpool_w16_sum
	v_lshlrev_b32_e32 v15, 16, v243
	v_add_f32_e32 v9, v9, v15
	s_cmp_le_i32 s4, 3
	s_cbranch_scc1 .Lpool_w16_sum
	v_lshlrev_b32_e32 v15, 16, v244
	v_add_f32_e32 v9, v9, v15
	s_cmp_le_i32 s4, 4
	s_cbranch_scc1 .Lpool_w16_sum
	v_lshlrev_b32_e32 v15, 16, v245
	v_add_f32_e32 v9, v9, v15
	s_cmp_le_i32 s4, 5
	s_cbranch_scc1 .Lpool_w16_sum
	v_lshlrev_b32_e32 v15, 16, v246
	v_add_f32_e32 v9, v9, v15
	s_cmp_le_i32 s4, 6
	s_cbranch_scc1 .Lpool_w16_sum
	v_lshlrev_b32_e32 v15, 16, v247
	v_add_f32_e32 v9, v9, v15
	s_cmp_le_i32 s4, 7
	s_cbranch_scc1 .Lpool_w16_sum
	v_lshlrev_b32_e32 v15, 16, v248
	v_add_f32_e32 v9, v9, v15
	s_cmp_le_i32 s4, 8
	s_cbranch_scc1 .Lpool_w16_sum
	v_lshlrev_b32_e32 v15, 16, v249
	v_add_f32_e32 v9, v9, v15
	s_cmp_le_i32 s4, 9
	s_cbranch_scc1 .Lpool_w16_sum
	v_lshlrev_b32_e32 v15, 16, v250
	v_add_f32_e32 v9, v9, v15
	s_cmp_le_i32 s4, 10
	s_cbranch_scc1 .Lpool_w16_sum
	v_lshlrev_b32_e32 v15, 16, v251
	v_add_f32_e32 v9, v9, v15
	s_cmp_le_i32 s4, 11
	s_cbranch_scc1 .Lpool_w16_sum
	v_lshlrev_b32_e32 v15, 16, v252
	v_add_f32_e32 v9, v9, v15
	s_cmp_le_i32 s4, 12
	s_cbranch_scc1 .Lpool_w16_sum
	v_lshlrev_b32_e32 v15, 16, v253
	v_add_f32_e32 v9, v9, v15
	s_cmp_le_i32 s4, 13
	s_cbranch_scc1 .Lpool_w16_sum
	v_lshlrev_b32_e32 v15, 16, v254
	v_add_f32_e32 v9, v9, v15
	s_cmp_le_i32 s4, 14
	s_cbranch_scc1 .Lpool_w16_sum
	v_lshlrev_b32_e32 v15, 16, v255
	v_add_f32_e32 v9, v9, v15
	s_cmp_le_i32 s4, 15
	s_cbranch_scc1 .Lpool_w16_sum
	v_lshlrev_b32_e32 v15, 16, v233
	v_add_f32_e32 v9, v9, v15

; __device__ __forceinline__ void pool_job(const Params& p, char* smem, int l, int seqrow0, int L, int t0) {
;     ...
;     const int g = tid >> 6, j = tid & 63;
;     const float* pw = p.pool_w + (size_t)(l * 4 + g) * 4096;
;     float acc[32];
; #pragma unroll
;     for (int tt = 0; tt < 32; ++tt) acc[tt] = 0.f;
;     for (int cch = 0; cch < 64; ++cch) {
;       float wv = pw[cch * 64 + j];
; #pragma unroll
;       for (int tt = 0; tt < 32; ++tt) acc[tt] += ds[tt * 256 + g * 64 + cch] * wv;
;     }
.LBB0_832:
	s_waitcnt vmcnt(0)
	global_load_dword v240, v[90:91], off offset:-256
	global_load_dword v241, v[90:91], off offset:0
	global_load_dword v242, v[90:91], off offset:256
	global_load_dword v243, v[90:91], off offset:512
	global_load_dword v244, v[90:91], off offset:768
	global_load_dword v245, v[90:91], off offset:1024
	global_load_dword v246, v[90:91], off offset:1280
	global_load_dword v247, v[90:91], off offset:1536
	global_load_dword v248, v[90:91], off offset:1792
	global_load_dword v249, v[90:91], off offset:2048
	global_load_dword v250, v[90:91], off offset:2304
	global_load_dword v251, v[90:91], off offset:2560
	global_load_dword v252, v[90:91], off offset:2816
	global_load_dword v253, v[90:91], off offset:3072
	global_load_dword v254, v[90:91], off offset:3328
	global_load_dword v255, v[90:91], off offset:3584
	s_mov_b64 s[12:13], 0x1000
	s_mov_b32 s5, 3
	v_lshl_add_u64 v[90:91], v[90:91], 0, s[12:13]
.Lpool_mv_pass:
	v_add_u32_e32 v232, s4, v0
	s_add_i32 s4, s4, 8
	ds_read2st64_b64 v[2:5], v232 offset0:0 offset1:2
	ds_read2st64_b64 v[6:9], v232 offset0:4 offset1:6
	ds_read2st64_b64 v[10:13], v232 offset0:8 offset1:10
	ds_read2st64_b64 v[14:17], v232 offset0:12 offset1:14
	ds_read2st64_b64 v[18:21], v232 offset0:16 offset1:18
	ds_read2st64_b64 v[22:25], v232 offset0:20 offset1:22
	ds_read2st64_b64 v[26:29], v232 offset0:24 offset1:26
	ds_read2st64_b64 v[30:33], v232 offset0:28 offset1:30
	ds_read2st64_b64 v[34:37], v232 offset0:32 offset1:34
	ds_read2st64_b64 v[38:41], v232 offset0:36 offset1:38
	ds_read2st64_b64 v[42:45], v232 offset0:40 offset1:42
	ds_read2st64_b64 v[46:49], v232 offset0:44 offset1:46
	ds_read2st64_b64 v[50:53], v232 offset0:48 offset1:50
	ds_read2st64_b64 v[54:57], v232 offset0:52 offset1:54
	ds_read2st64_b64 v[58:61], v232 offset0:56 offset1:58
	ds_read2st64_b64 v[62:65], v232 offset0:60 offset1:62
	s_waitcnt vmcnt(14)
	s_waitcnt lgkmcnt(12)
	v_fmac_f32_e32 v100, v240, v2
	v_fmac_f32_e32 v101, v240, v4
	v_fmac_f32_e32 v100, v241, v3
	v_fmac_f32_e32 v101, v241, v5
	v_fmac_f32_e32 v98, v240, v6
	v_fmac_f32_e32 v99, v240, v8
	v_fmac_f32_e32 v98, v241, v7
	v_fmac_f32_e32 v99, v241, v9
	v_fmac_f32_e32 v96, v240, v10
	v_fmac_f32_e32 v97, v240, v12
	v_fmac_f32_e32 v96, v241, v11
	v_fmac_f32_e32 v97, v241, v13
	v_fmac_f32_e32 v94, v240, v14
	v_fmac_f32_e32 v95, v240, v16
	v_fmac_f32_e32 v94, v241, v15
	v_fmac_f32_e32 v95, v241, v17
	s_waitcnt lgkmcnt(8)
	v_fmac_f32_e32 v92, v240, v18
	v_fmac_f32_e32 v93, v240, v20
	v_fmac_f32_e32 v92, v241, v19
	v_fmac_f32_e32 v93, v241, v21
	v_fmac_f32_e32 v88, v240, v22
	v_fmac_f32_e32 v89, v240, v24
	v_fmac_f32_e32 v88, v241, v23
	v_fmac_f32_e32 v89, v241, v25
	v_fmac_f32_e32 v86, v240, v26
	v_fmac_f32_e32 v87, v240, v28
	v_fmac_f32_e32 v86, v241, v27
	v_fmac_f32_e32 v87, v241, v29
	v_fmac_f32_e32 v84, v240, v30
	v_fmac_f32_e32 v85, v240, v32
	v_fmac_f32_e32 v84, v241, v31
	v_fmac_f32_e32 v85, v241, v33
	s_waitcnt lgkmcnt(4)
	v_fmac_f32_e32 v82, v240, v34
	v_fmac_f32_e32 v83, v240, v36
	v_fmac_f32_e32 v82, v241, v35
	v_fmac_f32_e32 v83, v241, v37
	v_fmac_f32_e32 v80, v240, v38
	v_fmac_f32_e32 v81, v240, v40
	v_fmac_f32_e32 v80, v241, v39
	v_fmac_f32_e32 v81, v241, v41
	v_fmac_f32_e32 v78, v240, v42
	v_fmac_f32_e32 v79, v240, v44
	v_fmac_f32_e32 v78, v241, v43
	v_fmac_f32_e32 v79, v241, v45
	v_fmac_f32_e32 v76, v240, v46
	v_fmac_f32_e32 v77, v240, v48
	v_fmac_f32_e32 v76, v241, v47
	v_fmac_f32_e32 v77, v241, v49
	s_waitcnt lgkmcnt(0)
	v_fmac_f32_e32 v74, v240, v50
	v_fmac_f32_e32 v75, v240, v52
	v_fmac_f32_e32 v74, v241, v51
	v_fmac_f32_e32 v75, v241, v53
	v_fmac_f32_e32 v72, v240, v54
	v_fmac_f32_e32 v73, v240, v56
	v_fmac_f32_e32 v72, v241, v55
	v_fmac_f32_e32 v73, v241, v57
	v_fmac_f32_e32 v70, v240, v58
	v_fmac_f32_e32 v71, v240, v60
	v_fmac_f32_e32 v70, v241, v59
	v_fmac_f32_e32 v71, v241, v61
	v_fmac_f32_e32 v68, v240, v62
	v_fmac_f32_e32 v69, v240, v64
	v_fmac_f32_e32 v68, v241, v63
	v_fmac_f32_e32 v69, v241, v65
	global_load_dword v240, v[90:91], off offset:-256
	global_load_dword v241, v[90:91], off offset:0
	v_add_u32_e32 v232, s4, v0
	s_add_i32 s4, s4, 8
	ds_read2st64_b64 v[2:5], v232 offset0:0 offset1:2
	ds_read2st64_b64 v[6:9], v232 offset0:4 offset1:6
	ds_read2st64_b64 v[10:13], v232 offset0:8 offset1:10
	ds_read2st64_b64 v[14:17], v232 offset0:12 offset1:14
	ds_read2st64_b64 v[18:21], v232 offset0:16 offset1:18
	ds_read2st64_b64 v[22:25], v232 offset0:20 offset1:22
	ds_read2st64_b64 v[26:29], v232 offset0:24 offset1:26
	ds_read2st64_b64 v[30:33], v232 offset0:28 offset1:30
	ds_read2st64_b64 v[34:37], v232 offset0:32 offset1:34
	ds_read2st64_b64 v[38:41], v232 offset0:36 offset1:38
	ds_read2st64_b64 v[42:45], v232 offset0:40 offset1:42
	ds_read2st64_b64 v[46:49], v232 offset0:44 offset1:46
	ds_read2st64_b64 v[50:53], v232 offset0:48 offset1:50
	ds_read2st64_b64 v[54:57], v232 offset0:52 offset1:54
	ds_read2st64_b64 v[58:61], v232 offset0:56 offset1:58
	ds_read2st64_b64 v[62:65], v232 offset0:60 offset1:62
	s_waitcnt vmcnt(14)
	s_waitcnt lgkmcnt(12)
	v_fmac_f32_e32 v100, v242, v2
	v_fmac_f32_e32 v101, v242, v4
	v_fmac_f32_e32 v100, v243, v3
	v_fmac_f32_e32 v101, v243, v5
	v_fmac_f32_e32 v98, v242, v6
	v_fmac_f32_e32 v99, v242, v8
	v_fmac_f32_e32 v98, v243, v7
	v_fmac_f32_e32 v99, v243, v9
	v_fmac_f32_e32 v96, v242, v10
	v_fmac_f32_e32 v97, v242, v12
	v_fmac_f32_e32 v96, v243, v11
	v_fmac_f32_e32 v97, v243, v13
	v_fmac_f32_e32 v94, v242, v14
	v_fmac_f32_e32 v95, v242, v16
	v_fmac_f32_e32 v94, v243, v15
	v_fmac_f32_e32 v95, v243, v17
	s_waitcnt lgkmcnt(8)
; __device__ __forceinline__ void pool_job(const Params& p, char* smem, int l, int seqrow0, int L, int t0) {
;     ...
;     const int g = tid >> 6, j = tid & 63;
;     const float* pw = p.pool_w + (size_t)(l * 4 + g) * 4096;
;     float acc[32];
; #pragma unroll
;     for (int tt = 0; tt < 32; ++tt) acc[tt] = 0.f;
;     for (int cch = 0; cch < 64; ++cch) {
;       float wv = pw[cch * 64 + j];
; #pragma unroll
;       for (int tt = 0; tt < 32; ++tt) acc[tt] += ds[tt * 256 + g * 64 + cch] * wv;
;     }
	v_fmac_f32_e32 v92, v242, v18
	v_fmac_f32_e32 v93, v242, v20
	v_fmac_f32_e32 v92, v243, v19
	v_fmac_f32_e32 v93, v243, v21
	v_fmac_f32_e32 v88, v242, v22
	v_fmac_f32_e32 v89, v242, v24
	v_fmac_f32_e32 v88, v243, v23
	v_fmac_f32_e32 v89, v243, v25
	v_fmac_f32_e32 v86, v242, v26
	v_fmac_f32_e32 v87, v242, v28
	v_fmac_f32_e32 v86, v243, v27
	v_fmac_f32_e32 v87, v243, v29
	v_fmac_f32_e32 v84, v242, v30
	v_fmac_f32_e32 v85, v242, v32
	v_fmac_f32_e32 v84, v243, v31
	v_fmac_f32_e32 v85, v243, v33
	s_waitcnt lgkmcnt(4)
	v_fmac_f32_e32 v82, v242, v34
	v_fmac_f32_e32 v83, v242, v36
	v_fmac_f32_e32 v82, v243, v35
	v_fmac_f32_e32 v83, v243, v37
	v_fmac_f32_e32 v80, v242, v38
	v_fmac_f32_e32 v81, v242, v40
	v_fmac_f32_e32 v80, v243, v39
	v_fmac_f32_e32 v81, v243, v41
	v_fmac_f32_e32 v78, v242, v42
	v_fmac_f32_e32 v79, v242, v44
	v_fmac_f32_e32 v78, v243, v43
	v_fmac_f32_e32 v79, v243, v45
	v_fmac_f32_e32 v76, v242, v46
	v_fmac_f32_e32 v77, v242, v48
	v_fmac_f32_e32 v76, v243, v47
	v_fmac_f32_e32 v77, v243, v49
	s_waitcnt lgkmcnt(0)
	v_fmac_f32_e32 v74, v242, v50
	v_fmac_f32_e32 v75, v242, v52
	v_fmac_f32_e32 v74, v243, v51
	v_fmac_f32_e32 v75, v243, v53
	v_fmac_f32_e32 v72, v242, v54
	v_fmac_f32_e32 v73, v242, v56
	v_fmac_f32_e32 v72, v243, v55
	v_fmac_f32_e32 v73, v243, v57
	v_fmac_f32_e32 v70, v242, v58
	v_fmac_f32_e32 v71, v242, v60
	v_fmac_f32_e32 v70, v243, v59
	v_fmac_f32_e32 v71, v243, v61
	v_fmac_f32_e32 v68, v242, v62
	v_fmac_f32_e32 v69, v242, v64
	v_fmac_f32_e32 v68, v243, v63
	v_fmac_f32_e32 v69, v243, v65
	global_load_dword v242, v[90:91], off offset:256
	global_load_dword v243, v[90:91], off offset:512
	v_add_u32_e32 v232, s4, v0
	s_add_i32 s4, s4, 8
	ds_read2st64_b64 v[2:5], v232 offset0:0 offset1:2
	ds_read2st64_b64 v[6:9], v232 offset0:4 offset1:6
	ds_read2st64_b64 v[10:13], v232 offset0:8 offset1:10
	ds_read2st64_b64 v[14:17], v232 offset0:12 offset1:14
	ds_read2st64_b64 v[18:21], v232 offset0:16 offset1:18
	ds_read2st64_b64 v[22:25], v232 offset0:20 offset1:22
	ds_read2st64_b64 v[26:29], v232 offset0:24 offset1:26
	ds_read2st64_b64 v[30:33], v232 offset0:28 offset1:30
	ds_read2st64_b64 v[34:37], v232 offset0:32 offset1:34
	ds_read2st64_b64 v[38:41], v232 offset0:36 offset1:38
	ds_read2st64_b64 v[42:45], v232 offset0:40 offset1:42
	ds_read2st64_b64 v[46:49], v232 offset0:44 offset1:46
	ds_read2st64_b64 v[50:53], v232 offset0:48 offset1:50
	ds_read2st64_b64 v[54:57], v232 offset0:52 offset1:54
	ds_read2st64_b64 v[58:61], v232 offset0:56 offset1:58
	ds_read2st64_b64 v[62:65], v232 offset0:60 offset1:62
	s_waitcnt vmcnt(14)
	s_waitcnt lgkmcnt(12)
	v_fmac_f32_e32 v100, v244, v2
	v_fmac_f32_e32 v101, v244, v4
	v_fmac_f32_e32 v100, v245, v3
	v_fmac_f32_e32 v101, v245, v5
	v_fmac_f32_e32 v98, v244, v6
	v_fmac_f32_e32 v99, v244, v8
	v_fmac_f32_e32 v98, v245, v7
	v_fmac_f32_e32 v99, v245, v9
	v_fmac_f32_e32 v96, v244, v10
	v_fmac_f32_e32 v97, v244, v12
	v_fmac_f32_e32 v96, v245, v11
	v_fmac_f32_e32 v97, v245, v13
	v_fmac_f32_e32 v94, v244, v14
	v_fmac_f32_e32 v95, v244, v16
	v_fmac_f32_e32 v94, v245, v15
	v_fmac_f32_e32 v95, v245, v17
	s_waitcnt lgkmcnt(8)
	v_fmac_f32_e32 v92, v244, v18
	v_fmac_f32_e32 v93, v244, v20
	v_fmac_f32_e32 v92, v245, v19
	v_fmac_f32_e32 v93, v245, v21
	v_fmac_f32_e32 v88, v244, v22
	v_fmac_f32_e32 v89, v244, v24
	v_fmac_f32_e32 v88, v245, v23
	v_fmac_f32_e32 v89, v245, v25
	v_fmac_f32_e32 v86, v244, v26
	v_fmac_f32_e32 v87, v244, v28
	v_fmac_f32_e32 v86, v245, v27
	v_fmac_f32_e32 v87, v245, v29
	v_fmac_f32_e32 v84, v244, v30
	v_fmac_f32_e32 v85, v244, v32
	v_fmac_f32_e32 v84, v245, v31
	v_fmac_f32_e32 v85, v245, v33
	s_waitcnt lgkmcnt(4)
	v_fmac_f32_e32 v82, v244, v34
	v_fmac_f32_e32 v83, v244, v36
	v_fmac_f32_e32 v82, v245, v35
	v_fmac_f32_e32 v83, v245, v37
	v_fmac_f32_e32 v80, v244, v38
	v_fmac_f32_e32 v81, v244, v40
	v_fmac_f32_e32 v80, v245, v39
	v_fmac_f32_e32 v81, v245, v41
	v_fmac_f32_e32 v78, v244, v42
	v_fmac_f32_e32 v79, v244, v44
	v_fmac_f32_e32 v78, v245, v43
	v_fmac_f32_e32 v79, v245, v45
	v_fmac_f32_e32 v76, v244, v46
	v_fmac_f32_e32 v77, v244, v48
	v_fmac_f32_e32 v76, v245, v47
	v_fmac_f32_e32 v77, v245, v49
	s_waitcnt lgkmcnt(0)
	v_fmac_f32_e32 v74, v244, v50
	v_fmac_f32_e32 v75, v244, v52
	v_fmac_f32_e32 v74, v245, v51
	v_fmac_f32_e32 v75, v245, v53
	v_fmac_f32_e32 v72, v244, v54
	v_fmac_f32_e32 v73, v244, v56
	v_fmac_f32_e32 v72, v245, v55
	v_fmac_f32_e32 v73, v245, v57
	v_fmac_f32_e32 v70, v244, v58
	v_fmac_f32_e32 v71, v244, v60
	v_fmac_f32_e32 v70, v245, v59
	v_fmac_f32_e32 v71, v245, v61
	v_fmac_f32_e32 v68, v244, v62
	v_fmac_f32_e32 v69, v244, v64
	v_fmac_f32_e32 v68, v245, v63
	v_fmac_f32_e32 v69, v245, v65
	global_load_dword v244, v[90:91], off offset:768
	global_load_dword v245, v[90:91], off offset:1024
	v_add_u32_e32 v232, s4, v0
	s_add_i32 s4, s4, 8
	ds_read2st64_b64 v[2:5], v232 offset0:0 offset1:2
	ds_read2st64_b64 v[6:9], v232 offset0:4 offset1:6
	ds_read2st64_b64 v[10:13], v232 offset0:8 offset1:10
	ds_read2st64_b64 v[14:17], v232 offset0:12 offset1:14
	ds_read2st64_b64 v[18:21], v232 offset0:16 offset1:18
	ds_read2st64_b64 v[22:25], v232 offset0:20 offset1:22
	ds_read2st64_b64 v[26:29], v232 offset0:24 offset1:26
	ds_read2st64_b64 v[30:33], v232 offset0:28 offset1:30
	ds_read2st64_b64 v[34:37], v232 offset0:32 offset1:34
	ds_read2st64_b64 v[38:41], v232 offset0:36 offset1:38
	ds_read2st64_b64 v[42:45], v232 offset0:40 offset1:42
	ds_read2st64_b64 v[46:49], v232 offset0:44 offset1:46
	ds_read2st64_b64 v[50:53], v232 offset0:48 offset1:50
	ds_read2st64_b64 v[54:57], v232 offset0:52 offset1:54
	ds_read2st64_b64 v[58:61], v232 offset0:56 offset1:58
	ds_read2st64_b64 v[62:65], v232 offset0:60 offset1:62
	s_waitcnt vmcnt(14)
; __device__ __forceinline__ void pool_job(const Params& p, char* smem, int l, int seqrow0, int L, int t0) {
;     ...
;     const int g = tid >> 6, j = tid & 63;
;     const float* pw = p.pool_w + (size_t)(l * 4 + g) * 4096;
;     float acc[32];
; #pragma unroll
;     for (int tt = 0; tt < 32; ++tt) acc[tt] = 0.f;
;     for (int cch = 0; cch < 64; ++cch) {
;       float wv = pw[cch * 64 + j];
; #pragma unroll
;       for (int tt = 0; tt < 32; ++tt) acc[tt] += ds[tt * 256 + g * 64 + cch] * wv;
;     }
	s_waitcnt lgkmcnt(12)
	v_fmac_f32_e32 v100, v246, v2
	v_fmac_f32_e32 v101, v246, v4
	v_fmac_f32_e32 v100, v247, v3
	v_fmac_f32_e32 v101, v247, v5
	v_fmac_f32_e32 v98, v246, v6
	v_fmac_f32_e32 v99, v246, v8
	v_fmac_f32_e32 v98, v247, v7
	v_fmac_f32_e32 v99, v247, v9
	v_fmac_f32_e32 v96, v246, v10
	v_fmac_f32_e32 v97, v246, v12
	v_fmac_f32_e32 v96, v247, v11
	v_fmac_f32_e32 v97, v247, v13
	v_fmac_f32_e32 v94, v246, v14
	v_fmac_f32_e32 v95, v246, v16
	v_fmac_f32_e32 v94, v247, v15
	v_fmac_f32_e32 v95, v247, v17
	s_waitcnt lgkmcnt(8)
	v_fmac_f32_e32 v92, v246, v18
	v_fmac_f32_e32 v93, v246, v20
	v_fmac_f32_e32 v92, v247, v19
	v_fmac_f32_e32 v93, v247, v21
	v_fmac_f32_e32 v88, v246, v22
	v_fmac_f32_e32 v89, v246, v24
	v_fmac_f32_e32 v88, v247, v23
	v_fmac_f32_e32 v89, v247, v25
	v_fmac_f32_e32 v86, v246, v26
	v_fmac_f32_e32 v87, v246, v28
	v_fmac_f32_e32 v86, v247, v27
	v_fmac_f32_e32 v87, v247, v29
	v_fmac_f32_e32 v84, v246, v30
	v_fmac_f32_e32 v85, v246, v32
	v_fmac_f32_e32 v84, v247, v31
	v_fmac_f32_e32 v85, v247, v33
	s_waitcnt lgkmcnt(4)
	v_fmac_f32_e32 v82, v246, v34
	v_fmac_f32_e32 v83, v246, v36
	v_fmac_f32_e32 v82, v247, v35
	v_fmac_f32_e32 v83, v247, v37
	v_fmac_f32_e32 v80, v246, v38
	v_fmac_f32_e32 v81, v246, v40
	v_fmac_f32_e32 v80, v247, v39
	v_fmac_f32_e32 v81, v247, v41
	v_fmac_f32_e32 v78, v246, v42
	v_fmac_f32_e32 v79, v246, v44
	v_fmac_f32_e32 v78, v247, v43
	v_fmac_f32_e32 v79, v247, v45
	v_fmac_f32_e32 v76, v246, v46
	v_fmac_f32_e32 v77, v246, v48
	v_fmac_f32_e32 v76, v247, v47
	v_fmac_f32_e32 v77, v247, v49
	s_waitcnt lgkmcnt(0)
	v_fmac_f32_e32 v74, v246, v50
	v_fmac_f32_e32 v75, v246, v52
	v_fmac_f32_e32 v74, v247, v51
	v_fmac_f32_e32 v75, v247, v53
	v_fmac_f32_e32 v72, v246, v54
	v_fmac_f32_e32 v73, v246, v56
	v_fmac_f32_e32 v72, v247, v55
	v_fmac_f32_e32 v73, v247, v57
	v_fmac_f32_e32 v70, v246, v58
	v_fmac_f32_e32 v71, v246, v60
	v_fmac_f32_e32 v70, v247, v59
	v_fmac_f32_e32 v71, v247, v61
	v_fmac_f32_e32 v68, v246, v62
	v_fmac_f32_e32 v69, v246, v64
	v_fmac_f32_e32 v68, v247, v63
	v_fmac_f32_e32 v69, v247, v65
	global_load_dword v246, v[90:91], off offset:1280
	global_load_dword v247, v[90:91], off offset:1536
	v_add_u32_e32 v232, s4, v0
	s_add_i32 s4, s4, 8
	ds_read2st64_b64 v[2:5], v232 offset0:0 offset1:2
	ds_read2st64_b64 v[6:9], v232 offset0:4 offset1:6
	ds_read2st64_b64 v[10:13], v232 offset0:8 offset1:10
	ds_read2st64_b64 v[14:17], v232 offset0:12 offset1:14
	ds_read2st64_b64 v[18:21], v232 offset0:16 offset1:18
	ds_read2st64_b64 v[22:25], v232 offset0:20 offset1:22
	ds_read2st64_b64 v[26:29], v232 offset0:24 offset1:26
	ds_read2st64_b64 v[30:33], v232 offset0:28 offset1:30
	ds_read2st64_b64 v[34:37], v232 offset0:32 offset1:34
	ds_read2st64_b64 v[38:41], v232 offset0:36 offset1:38
	ds_read2st64_b64 v[42:45], v232 offset0:40 offset1:42
	ds_read2st64_b64 v[46:49], v232 offset0:44 offset1:46
	ds_read2st64_b64 v[50:53], v232 offset0:48 offset1:50
	ds_read2st64_b64 v[54:57], v232 offset0:52 offset1:54
	ds_read2st64_b64 v[58:61], v232 offset0:56 offset1:58
	ds_read2st64_b64 v[62:65], v232 offset0:60 offset1:62
	s_waitcnt vmcnt(14)
	s_waitcnt lgkmcnt(12)
	v_fmac_f32_e32 v100, v248, v2
	v_fmac_f32_e32 v101, v248, v4
	v_fmac_f32_e32 v100, v249, v3
	v_fmac_f32_e32 v101, v249, v5
	v_fmac_f32_e32 v98, v248, v6
	v_fmac_f32_e32 v99, v248, v8
	v_fmac_f32_e32 v98, v249, v7
	v_fmac_f32_e32 v99, v249, v9
	v_fmac_f32_e32 v96, v248, v10
	v_fmac_f32_e32 v97, v248, v12
	v_fmac_f32_e32 v96, v249, v11
	v_fmac_f32_e32 v97, v249, v13
	v_fmac_f32_e32 v94, v248, v14
	v_fmac_f32_e32 v95, v248, v16
	v_fmac_f32_e32 v94, v249, v15
	v_fmac_f32_e32 v95, v249, v17
	s_waitcnt lgkmcnt(8)
	v_fmac_f32_e32 v92, v248, v18
	v_fmac_f32_e32 v93, v248, v20
	v_fmac_f32_e32 v92, v249, v19
	v_fmac_f32_e32 v93, v249, v21
	v_fmac_f32_e32 v88, v248, v22
	v_fmac_f32_e32 v89, v248, v24
	v_fmac_f32_e32 v88, v249, v23
	v_fmac_f32_e32 v89, v249, v25
	v_fmac_f32_e32 v86, v248, v26
	v_fmac_f32_e32 v87, v248, v28
	v_fmac_f32_e32 v86, v249, v27
	v_fmac_f32_e32 v87, v249, v29
	v_fmac_f32_e32 v84, v248, v30
	v_fmac_f32_e32 v85, v248, v32
	v_fmac_f32_e32 v84, v249, v31
	v_fmac_f32_e32 v85, v249, v33
	s_waitcnt lgkmcnt(4)
	v_fmac_f32_e32 v82, v248, v34
	v_fmac_f32_e32 v83, v248, v36
	v_fmac_f32_e32 v82, v249, v35
	v_fmac_f32_e32 v83, v249, v37
	v_fmac_f32_e32 v80, v248, v38
	v_fmac_f32_e32 v81, v248, v40
	v_fmac_f32_e32 v80, v249, v39
	v_fmac_f32_e32 v81, v249, v41
	v_fmac_f32_e32 v78, v248, v42
	v_fmac_f32_e32 v79, v248, v44
	v_fmac_f32_e32 v78, v249, v43
	v_fmac_f32_e32 v79, v249, v45
	v_fmac_f32_e32 v76, v248, v46
	v_fmac_f32_e32 v77, v248, v48
	v_fmac_f32_e32 v76, v249, v47
	v_fmac_f32_e32 v77, v249, v49
	s_waitcnt lgkmcnt(0)
	v_fmac_f32_e32 v74, v248, v50
	v_fmac_f32_e32 v75, v248, v52
	v_fmac_f32_e32 v74, v249, v51
	v_fmac_f32_e32 v75, v249, v53
	v_fmac_f32_e32 v72, v248, v54
	v_fmac_f32_e32 v73, v248, v56
	v_fmac_f32_e32 v72, v249, v55
	v_fmac_f32_e32 v73, v249, v57
	v_fmac_f32_e32 v70, v248, v58
	v_fmac_f32_e32 v71, v248, v60
	v_fmac_f32_e32 v70, v249, v59
	v_fmac_f32_e32 v71, v249, v61
	v_fmac_f32_e32 v68, v248, v62
	v_fmac_f32_e32 v69, v248, v64
	v_fmac_f32_e32 v68, v249, v63
	v_fmac_f32_e32 v69, v249, v65
	global_load_dword v248, v[90:91], off offset:1792
	global_load_dword v249, v[90:91], off offset:2048
	v_add_u32_e32 v232, s4, v0
	s_add_i32 s4, s4, 8
	ds_read2st64_b64 v[2:5], v232 offset0:0 offset1:2
	ds_read2st64_b64 v[6:9], v232 offset0:4 offset1:6
	ds_read2st64_b64 v[10:13], v232 offset0:8 offset1:10
	ds_read2st64_b64 v[14:17], v232 offset0:12 offset1:14
	ds_read2st64_b64 v[18:21], v232 offset0:16 offset1:18
	ds_read2st64_b64 v[22:25], v232 offset0:20 offset1:22
	ds_read2st64_b64 v[26:29], v232 offset0:24 offset1:26
	ds_read2st64_b64 v[30:33], v232 offset0:28 offset1:30
	ds_read2st64_b64 v[34:37], v232 offset0:32 offset1:34
	ds_read2st64_b64 v[38:41], v232 offset0:36 offset1:38
	ds_read2st64_b64 v[42:45], v232 offset0:40 offset1:42
	ds_read2st64_b64 v[46:49], v232 offset0:44 offset1:46
	ds_read2st64_b64 v[50:53], v232 offset0:48 offset1:50
	ds_read2st64_b64 v[54:57], v232 offset0:52 offset1:54
	ds_read2st64_b64 v[58:61], v232 offset0:56 offset1:58
	ds_read2st64_b64 v[62:65], v232 offset0:60 offset1:62
	s_waitcnt vmcnt(14)
; __device__ __forceinline__ void pool_job(const Params& p, char* smem, int l, int seqrow0, int L, int t0) {
;     ...
;     const int g = tid >> 6, j = tid & 63;
;     const float* pw = p.pool_w + (size_t)(l * 4 + g) * 4096;
;     float acc[32];
; #pragma unroll
;     for (int tt = 0; tt < 32; ++tt) acc[tt] = 0.f;
;     for (int cch = 0; cch < 64; ++cch) {
;       float wv = pw[cch * 64 + j];
; #pragma unroll
;       for (int tt = 0; tt < 32; ++tt) acc[tt] += ds[tt * 256 + g * 64 + cch] * wv;
;     }
	s_waitcnt lgkmcnt(12)
	v_fmac_f32_e32 v100, v250, v2
	v_fmac_f32_e32 v101, v250, v4
	v_fmac_f32_e32 v100, v251, v3
	v_fmac_f32_e32 v101, v251, v5
	v_fmac_f32_e32 v98, v250, v6
	v_fmac_f32_e32 v99, v250, v8
	v_fmac_f32_e32 v98, v251, v7
	v_fmac_f32_e32 v99, v251, v9
	v_fmac_f32_e32 v96, v250, v10
	v_fmac_f32_e32 v97, v250, v12
	v_fmac_f32_e32 v96, v251, v11
	v_fmac_f32_e32 v97, v251, v13
	v_fmac_f32_e32 v94, v250, v14
	v_fmac_f32_e32 v95, v250, v16
	v_fmac_f32_e32 v94, v251, v15
	v_fmac_f32_e32 v95, v251, v17
	s_waitcnt lgkmcnt(8)
	v_fmac_f32_e32 v92, v250, v18
	v_fmac_f32_e32 v93, v250, v20
	v_fmac_f32_e32 v92, v251, v19
	v_fmac_f32_e32 v93, v251, v21
	v_fmac_f32_e32 v88, v250, v22
	v_fmac_f32_e32 v89, v250, v24
	v_fmac_f32_e32 v88, v251, v23
	v_fmac_f32_e32 v89, v251, v25
	v_fmac_f32_e32 v86, v250, v26
	v_fmac_f32_e32 v87, v250, v28
	v_fmac_f32_e32 v86, v251, v27
	v_fmac_f32_e32 v87, v251, v29
	v_fmac_f32_e32 v84, v250, v30
	v_fmac_f32_e32 v85, v250, v32
	v_fmac_f32_e32 v84, v251, v31
	v_fmac_f32_e32 v85, v251, v33
	s_waitcnt lgkmcnt(4)
	v_fmac_f32_e32 v82, v250, v34
	v_fmac_f32_e32 v83, v250, v36
	v_fmac_f32_e32 v82, v251, v35
	v_fmac_f32_e32 v83, v251, v37
	v_fmac_f32_e32 v80, v250, v38
	v_fmac_f32_e32 v81, v250, v40
	v_fmac_f32_e32 v80, v251, v39
	v_fmac_f32_e32 v81, v251, v41
	v_fmac_f32_e32 v78, v250, v42
	v_fmac_f32_e32 v79, v250, v44
	v_fmac_f32_e32 v78, v251, v43
	v_fmac_f32_e32 v79, v251, v45
	v_fmac_f32_e32 v76, v250, v46
	v_fmac_f32_e32 v77, v250, v48
	v_fmac_f32_e32 v76, v251, v47
	v_fmac_f32_e32 v77, v251, v49
	s_waitcnt lgkmcnt(0)
	v_fmac_f32_e32 v74, v250, v50
	v_fmac_f32_e32 v75, v250, v52
	v_fmac_f32_e32 v74, v251, v51
	v_fmac_f32_e32 v75, v251, v53
	v_fmac_f32_e32 v72, v250, v54
	v_fmac_f32_e32 v73, v250, v56
	v_fmac_f32_e32 v72, v251, v55
	v_fmac_f32_e32 v73, v251, v57
	v_fmac_f32_e32 v70, v250, v58
	v_fmac_f32_e32 v71, v250, v60
	v_fmac_f32_e32 v70, v251, v59
	v_fmac_f32_e32 v71, v251, v61
	v_fmac_f32_e32 v68, v250, v62
	v_fmac_f32_e32 v69, v250, v64
	v_fmac_f32_e32 v68, v251, v63
	v_fmac_f32_e32 v69, v251, v65
	global_load_dword v250, v[90:91], off offset:2304
	global_load_dword v251, v[90:91], off offset:2560
	v_add_u32_e32 v232, s4, v0
	s_add_i32 s4, s4, 8
	ds_read2st64_b64 v[2:5], v232 offset0:0 offset1:2
	ds_read2st64_b64 v[6:9], v232 offset0:4 offset1:6
	ds_read2st64_b64 v[10:13], v232 offset0:8 offset1:10
	ds_read2st64_b64 v[14:17], v232 offset0:12 offset1:14
	ds_read2st64_b64 v[18:21], v232 offset0:16 offset1:18
	ds_read2st64_b64 v[22:25], v232 offset0:20 offset1:22
	ds_read2st64_b64 v[26:29], v232 offset0:24 offset1:26
	ds_read2st64_b64 v[30:33], v232 offset0:28 offset1:30
	ds_read2st64_b64 v[34:37], v232 offset0:32 offset1:34
	ds_read2st64_b64 v[38:41], v232 offset0:36 offset1:38
	ds_read2st64_b64 v[42:45], v232 offset0:40 offset1:42
	ds_read2st64_b64 v[46:49], v232 offset0:44 offset1:46
	ds_read2st64_b64 v[50:53], v232 offset0:48 offset1:50
	ds_read2st64_b64 v[54:57], v232 offset0:52 offset1:54
	ds_read2st64_b64 v[58:61], v232 offset0:56 offset1:58
	ds_read2st64_b64 v[62:65], v232 offset0:60 offset1:62
	s_waitcnt vmcnt(14)
	s_waitcnt lgkmcnt(12)
	v_fmac_f32_e32 v100, v252, v2
	v_fmac_f32_e32 v101, v252, v4
	v_fmac_f32_e32 v100, v253, v3
	v_fmac_f32_e32 v101, v253, v5
	v_fmac_f32_e32 v98, v252, v6
	v_fmac_f32_e32 v99, v252, v8
	v_fmac_f32_e32 v98, v253, v7
	v_fmac_f32_e32 v99, v253, v9
	v_fmac_f32_e32 v96, v252, v10
	v_fmac_f32_e32 v97, v252, v12
	v_fmac_f32_e32 v96, v253, v11
	v_fmac_f32_e32 v97, v253, v13
	v_fmac_f32_e32 v94, v252, v14
	v_fmac_f32_e32 v95, v252, v16
	v_fmac_f32_e32 v94, v253, v15
	v_fmac_f32_e32 v95, v253, v17
	s_waitcnt lgkmcnt(8)
	v_fmac_f32_e32 v92, v252, v18
	v_fmac_f32_e32 v93, v252, v20
	v_fmac_f32_e32 v92, v253, v19
	v_fmac_f32_e32 v93, v253, v21
	v_fmac_f32_e32 v88, v252, v22
	v_fmac_f32_e32 v89, v252, v24
	v_fmac_f32_e32 v88, v253, v23
	v_fmac_f32_e32 v89, v253, v25
	v_fmac_f32_e32 v86, v252, v26
	v_fmac_f32_e32 v87, v252, v28
	v_fmac_f32_e32 v86, v253, v27
	v_fmac_f32_e32 v87, v253, v29
	v_fmac_f32_e32 v84, v252, v30
	v_fmac_f32_e32 v85, v252, v32
	v_fmac_f32_e32 v84, v253, v31
	v_fmac_f32_e32 v85, v253, v33
	s_waitcnt lgkmcnt(4)
	v_fmac_f32_e32 v82, v252, v34
	v_fmac_f32_e32 v83, v252, v36
	v_fmac_f32_e32 v82, v253, v35
	v_fmac_f32_e32 v83, v253, v37
	v_fmac_f32_e32 v80, v252, v38
	v_fmac_f32_e32 v81, v252, v40
	v_fmac_f32_e32 v80, v253, v39
	v_fmac_f32_e32 v81, v253, v41
	v_fmac_f32_e32 v78, v252, v42
	v_fmac_f32_e32 v79, v252, v44
	v_fmac_f32_e32 v78, v253, v43
	v_fmac_f32_e32 v79, v253, v45
	v_fmac_f32_e32 v76, v252, v46
	v_fmac_f32_e32 v77, v252, v48
	v_fmac_f32_e32 v76, v253, v47
	v_fmac_f32_e32 v77, v253, v49
	s_waitcnt lgkmcnt(0)
	v_fmac_f32_e32 v74, v252, v50
	v_fmac_f32_e32 v75, v252, v52
	v_fmac_f32_e32 v74, v253, v51
	v_fmac_f32_e32 v75, v253, v53
	v_fmac_f32_e32 v72, v252, v54
	v_fmac_f32_e32 v73, v252, v56
	v_fmac_f32_e32 v72, v253, v55
	v_fmac_f32_e32 v73, v253, v57
	v_fmac_f32_e32 v70, v252, v58
	v_fmac_f32_e32 v71, v252, v60
	v_fmac_f32_e32 v70, v253, v59
	v_fmac_f32_e32 v71, v253, v61
	v_fmac_f32_e32 v68, v252, v62
	v_fmac_f32_e32 v69, v252, v64
	v_fmac_f32_e32 v68, v253, v63
	v_fmac_f32_e32 v69, v253, v65
	global_load_dword v252, v[90:91], off offset:2816
	global_load_dword v253, v[90:91], off offset:3072
	v_add_u32_e32 v232, s4, v0
	s_add_i32 s4, s4, 8
	ds_read2st64_b64 v[2:5], v232 offset0:0 offset1:2
	ds_read2st64_b64 v[6:9], v232 offset0:4 offset1:6
	ds_read2st64_b64 v[10:13], v232 offset0:8 offset1:10
	ds_read2st64_b64 v[14:17], v232 offset0:12 offset1:14
	ds_read2st64_b64 v[18:21], v232 offset0:16 offset1:18
	ds_read2st64_b64 v[22:25], v232 offset0:20 offset1:22
	ds_read2st64_b64 v[26:29], v232 offset0:24 offset1:26
	ds_read2st64_b64 v[30:33], v232 offset0:28 offset1:30
	ds_read2st64_b64 v[34:37], v232 offset0:32 offset1:34
	ds_read2st64_b64 v[38:41], v232 offset0:36 offset1:38
	ds_read2st64_b64 v[42:45], v232 offset0:40 offset1:42
	ds_read2st64_b64 v[46:49], v232 offset0:44 offset1:46
	ds_read2st64_b64 v[50:53], v232 offset0:48 offset1:50
	ds_read2st64_b64 v[54:57], v232 offset0:52 offset1:54
	ds_read2st64_b64 v[58:61], v232 offset0:56 offset1:58
	ds_read2st64_b64 v[62:65], v232 offset0:60 offset1:62
	s_waitcnt vmcnt(14)
; __device__ __forceinline__ void pool_job(const Params& p, char* smem, int l, int seqrow0, int L, int t0) {
;     ...
;     const int g = tid >> 6, j = tid & 63;
;     const float* pw = p.pool_w + (size_t)(l * 4 + g) * 4096;
;     float acc[32];
; #pragma unroll
;     for (int tt = 0; tt < 32; ++tt) acc[tt] = 0.f;
;     for (int cch = 0; cch < 64; ++cch) {
;       float wv = pw[cch * 64 + j];
; #pragma unroll
;       for (int tt = 0; tt < 32; ++tt) acc[tt] += ds[tt * 256 + g * 64 + cch] * wv;
;     }
	s_waitcnt lgkmcnt(12)
	v_fmac_f32_e32 v100, v254, v2
	v_fmac_f32_e32 v101, v254, v4
	v_fmac_f32_e32 v100, v255, v3
	v_fmac_f32_e32 v101, v255, v5
	v_fmac_f32_e32 v98, v254, v6
	v_fmac_f32_e32 v99, v254, v8
	v_fmac_f32_e32 v98, v255, v7
	v_fmac_f32_e32 v99, v255, v9
	v_fmac_f32_e32 v96, v254, v10
	v_fmac_f32_e32 v97, v254, v12
	v_fmac_f32_e32 v96, v255, v11
	v_fmac_f32_e32 v97, v255, v13
	v_fmac_f32_e32 v94, v254, v14
	v_fmac_f32_e32 v95, v254, v16
	v_fmac_f32_e32 v94, v255, v15
	v_fmac_f32_e32 v95, v255, v17
	s_waitcnt lgkmcnt(8)
	v_fmac_f32_e32 v92, v254, v18
	v_fmac_f32_e32 v93, v254, v20
	v_fmac_f32_e32 v92, v255, v19
	v_fmac_f32_e32 v93, v255, v21
	v_fmac_f32_e32 v88, v254, v22
	v_fmac_f32_e32 v89, v254, v24
	v_fmac_f32_e32 v88, v255, v23
	v_fmac_f32_e32 v89, v255, v25
	v_fmac_f32_e32 v86, v254, v26
	v_fmac_f32_e32 v87, v254, v28
	v_fmac_f32_e32 v86, v255, v27
	v_fmac_f32_e32 v87, v255, v29
	v_fmac_f32_e32 v84, v254, v30
	v_fmac_f32_e32 v85, v254, v32
	v_fmac_f32_e32 v84, v255, v31
	v_fmac_f32_e32 v85, v255, v33
	s_waitcnt lgkmcnt(4)
	v_fmac_f32_e32 v82, v254, v34
	v_fmac_f32_e32 v83, v254, v36
	v_fmac_f32_e32 v82, v255, v35
	v_fmac_f32_e32 v83, v255, v37
	v_fmac_f32_e32 v80, v254, v38
	v_fmac_f32_e32 v81, v254, v40
	v_fmac_f32_e32 v80, v255, v39
	v_fmac_f32_e32 v81, v255, v41
	v_fmac_f32_e32 v78, v254, v42
	v_fmac_f32_e32 v79, v254, v44
	v_fmac_f32_e32 v78, v255, v43
	v_fmac_f32_e32 v79, v255, v45
	v_fmac_f32_e32 v76, v254, v46
	v_fmac_f32_e32 v77, v254, v48
	v_fmac_f32_e32 v76, v255, v47
	v_fmac_f32_e32 v77, v255, v49
	s_waitcnt lgkmcnt(0)
	v_fmac_f32_e32 v74, v254, v50
	v_fmac_f32_e32 v75, v254, v52
	v_fmac_f32_e32 v74, v255, v51
	v_fmac_f32_e32 v75, v255, v53
	v_fmac_f32_e32 v72, v254, v54
	v_fmac_f32_e32 v73, v254, v56
	v_fmac_f32_e32 v72, v255, v55
	v_fmac_f32_e32 v73, v255, v57
	v_fmac_f32_e32 v70, v254, v58
	v_fmac_f32_e32 v71, v254, v60
	v_fmac_f32_e32 v70, v255, v59
	v_fmac_f32_e32 v71, v255, v61
	v_fmac_f32_e32 v68, v254, v62
	v_fmac_f32_e32 v69, v254, v64
	v_fmac_f32_e32 v68, v255, v63
	v_fmac_f32_e32 v69, v255, v65
	global_load_dword v254, v[90:91], off offset:3328
	global_load_dword v255, v[90:91], off offset:3584
	v_lshl_add_u64 v[90:91], v[90:91], 0, s[12:13]
	s_sub_u32 s5, s5, 1
	s_cmp_lg_u32 s5, 0
	s_cbranch_scc1 .Lpool_mv_pass
	v_add_u32_e32 v232, s4, v0
	s_add_i32 s4, s4, 8
	ds_read2st64_b64 v[2:5], v232 offset0:0 offset1:2
	ds_read2st64_b64 v[6:9], v232 offset0:4 offset1:6
	ds_read2st64_b64 v[10:13], v232 offset0:8 offset1:10
	ds_read2st64_b64 v[14:17], v232 offset0:12 offset1:14
	ds_read2st64_b64 v[18:21], v232 offset0:16 offset1:18
	ds_read2st64_b64 v[22:25], v232 offset0:20 offset1:22
	ds_read2st64_b64 v[26:29], v232 offset0:24 offset1:26
	ds_read2st64_b64 v[30:33], v232 offset0:28 offset1:30
	ds_read2st64_b64 v[34:37], v232 offset0:32 offset1:34
	ds_read2st64_b64 v[38:41], v232 offset0:36 offset1:38
	ds_read2st64_b64 v[42:45], v232 offset0:40 offset1:42
	ds_read2st64_b64 v[46:49], v232 offset0:44 offset1:46
	ds_read2st64_b64 v[50:53], v232 offset0:48 offset1:50
	ds_read2st64_b64 v[54:57], v232 offset0:52 offset1:54
	ds_read2st64_b64 v[58:61], v232 offset0:56 offset1:58
	ds_read2st64_b64 v[62:65], v232 offset0:60 offset1:62
	s_waitcnt vmcnt(0)
	s_waitcnt lgkmcnt(12)
	v_fmac_f32_e32 v100, v240, v2
	v_fmac_f32_e32 v101, v240, v4
	v_fmac_f32_e32 v100, v241, v3
	v_fmac_f32_e32 v101, v241, v5
	v_fmac_f32_e32 v98, v240, v6
	v_fmac_f32_e32 v99, v240, v8
	v_fmac_f32_e32 v98, v241, v7
	v_fmac_f32_e32 v99, v241, v9
	v_fmac_f32_e32 v96, v240, v10
	v_fmac_f32_e32 v97, v240, v12
	v_fmac_f32_e32 v96, v241, v11
	v_fmac_f32_e32 v97, v241, v13
	v_fmac_f32_e32 v94, v240, v14
	v_fmac_f32_e32 v95, v240, v16
	v_fmac_f32_e32 v94, v241, v15
	v_fmac_f32_e32 v95, v241, v17
	s_waitcnt lgkmcnt(8)
	v_fmac_f32_e32 v92, v240, v18
	v_fmac_f32_e32 v93, v240, v20
	v_fmac_f32_e32 v92, v241, v19
	v_fmac_f32_e32 v93, v241, v21
	v_fmac_f32_e32 v88, v240, v22
	v_fmac_f32_e32 v89, v240, v24
	v_fmac_f32_e32 v88, v241, v23
	v_fmac_f32_e32 v89, v241, v25
	v_fmac_f32_e32 v86, v240, v26
	v_fmac_f32_e32 v87, v240, v28
	v_fmac_f32_e32 v86, v241, v27
	v_fmac_f32_e32 v87, v241, v29
	v_fmac_f32_e32 v84, v240, v30
	v_fmac_f32_e32 v85, v240, v32
	v_fmac_f32_e32 v84, v241, v31
	v_fmac_f32_e32 v85, v241, v33
	s_waitcnt lgkmcnt(4)
	v_fmac_f32_e32 v82, v240, v34
	v_fmac_f32_e32 v83, v240, v36
	v_fmac_f32_e32 v82, v241, v35
	v_fmac_f32_e32 v83, v241, v37
	v_fmac_f32_e32 v80, v240, v38
	v_fmac_f32_e32 v81, v240, v40
	v_fmac_f32_e32 v80, v241, v39
	v_fmac_f32_e32 v81, v241, v41
	v_fmac_f32_e32 v78, v240, v42
	v_fmac_f32_e32 v79, v240, v44
	v_fmac_f32_e32 v78, v241, v43
	v_fmac_f32_e32 v79, v241, v45
	v_fmac_f32_e32 v76, v240, v46
	v_fmac_f32_e32 v77, v240, v48
	v_fmac_f32_e32 v76, v241, v47
	v_fmac_f32_e32 v77, v241, v49
	s_waitcnt lgkmcnt(0)
	v_fmac_f32_e32 v74, v240, v50
	v_fmac_f32_e32 v75, v240, v52
	v_fmac_f32_e32 v74, v241, v51
	v_fmac_f32_e32 v75, v241, v53
	v_fmac_f32_e32 v72, v240, v54
	v_fmac_f32_e32 v73, v240, v56
	v_fmac_f32_e32 v72, v241, v55
	v_fmac_f32_e32 v73, v241, v57
	v_fmac_f32_e32 v70, v240, v58
	v_fmac_f32_e32 v71, v240, v60
	v_fmac_f32_e32 v70, v241, v59
	v_fmac_f32_e32 v71, v241, v61
	v_fmac_f32_e32 v68, v240, v62
	v_fmac_f32_e32 v69, v240, v64
	v_fmac_f32_e32 v68, v241, v63
	v_fmac_f32_e32 v69, v241, v65
	v_add_u32_e32 v232, s4, v0
	s_add_i32 s4, s4, 8
	ds_read2st64_b64 v[2:5], v232 offset0:0 offset1:2
	ds_read2st64_b64 v[6:9], v232 offset0:4 offset1:6
	ds_read2st64_b64 v[10:13], v232 offset0:8 offset1:10
	ds_read2st64_b64 v[14:17], v232 offset0:12 offset1:14
	ds_read2st64_b64 v[18:21], v232 offset0:16 offset1:18
	ds_read2st64_b64 v[22:25], v232 offset0:20 offset1:22
	ds_read2st64_b64 v[26:29], v232 offset0:24 offset1:26
	ds_read2st64_b64 v[30:33], v232 offset0:28 offset1:30
	ds_read2st64_b64 v[34:37], v232 offset0:32 offset1:34
	ds_read2st64_b64 v[38:41], v232 offset0:36 offset1:38
	ds_read2st64_b64 v[42:45], v232 offset0:40 offset1:42
	ds_read2st64_b64 v[46:49], v232 offset0:44 offset1:46
	ds_read2st64_b64 v[50:53], v232 offset0:48 offset1:50
	ds_read2st64_b64 v[54:57], v232 offset0:52 offset1:54
	ds_read2st64_b64 v[58:61], v232 offset0:56 offset1:58
	ds_read2st64_b64 v[62:65], v232 offset0:60 offset1:62
	s_waitcnt lgkmcnt(12)
; __device__ __forceinline__ void pool_job(const Params& p, char* smem, int l, int seqrow0, int L, int t0) {
;     ...
;     const int g = tid >> 6, j = tid & 63;
;     const float* pw = p.pool_w + (size_t)(l * 4 + g) * 4096;
;     float acc[32];
; #pragma unroll
;     for (int tt = 0; tt < 32; ++tt) acc[tt] = 0.f;
;     for (int cch = 0; cch < 64; ++cch) {
;       float wv = pw[cch * 64 + j];
; #pragma unroll
;       for (int tt = 0; tt < 32; ++tt) acc[tt] += ds[tt * 256 + g * 64 + cch] * wv;
;     }
	v_fmac_f32_e32 v100, v242, v2
	v_fmac_f32_e32 v101, v242, v4
	v_fmac_f32_e32 v100, v243, v3
	v_fmac_f32_e32 v101, v243, v5
	v_fmac_f32_e32 v98, v242, v6
	v_fmac_f32_e32 v99, v242, v8
	v_fmac_f32_e32 v98, v243, v7
	v_fmac_f32_e32 v99, v243, v9
	v_fmac_f32_e32 v96, v242, v10
	v_fmac_f32_e32 v97, v242, v12
	v_fmac_f32_e32 v96, v243, v11
	v_fmac_f32_e32 v97, v243, v13
	v_fmac_f32_e32 v94, v242, v14
	v_fmac_f32_e32 v95, v242, v16
	v_fmac_f32_e32 v94, v243, v15
	v_fmac_f32_e32 v95, v243, v17
	s_waitcnt lgkmcnt(8)
	v_fmac_f32_e32 v92, v242, v18
	v_fmac_f32_e32 v93, v242, v20
	v_fmac_f32_e32 v92, v243, v19
	v_fmac_f32_e32 v93, v243, v21
	v_fmac_f32_e32 v88, v242, v22
	v_fmac_f32_e32 v89, v242, v24
	v_fmac_f32_e32 v88, v243, v23
	v_fmac_f32_e32 v89, v243, v25
	v_fmac_f32_e32 v86, v242, v26
	v_fmac_f32_e32 v87, v242, v28
	v_fmac_f32_e32 v86, v243, v27
	v_fmac_f32_e32 v87, v243, v29
	v_fmac_f32_e32 v84, v242, v30
	v_fmac_f32_e32 v85, v242, v32
	v_fmac_f32_e32 v84, v243, v31
	v_fmac_f32_e32 v85, v243, v33
	s_waitcnt lgkmcnt(4)
	v_fmac_f32_e32 v82, v242, v34
	v_fmac_f32_e32 v83, v242, v36
	v_fmac_f32_e32 v82, v243, v35
	v_fmac_f32_e32 v83, v243, v37
	v_fmac_f32_e32 v80, v242, v38
	v_fmac_f32_e32 v81, v242, v40
	v_fmac_f32_e32 v80, v243, v39
	v_fmac_f32_e32 v81, v243, v41
	v_fmac_f32_e32 v78, v242, v42
	v_fmac_f32_e32 v79, v242, v44
	v_fmac_f32_e32 v78, v243, v43
	v_fmac_f32_e32 v79, v243, v45
	v_fmac_f32_e32 v76, v242, v46
	v_fmac_f32_e32 v77, v242, v48
	v_fmac_f32_e32 v76, v243, v47
	v_fmac_f32_e32 v77, v243, v49
	s_waitcnt lgkmcnt(0)
	v_fmac_f32_e32 v74, v242, v50
	v_fmac_f32_e32 v75, v242, v52
	v_fmac_f32_e32 v74, v243, v51
	v_fmac_f32_e32 v75, v243, v53
	v_fmac_f32_e32 v72, v242, v54
	v_fmac_f32_e32 v73, v242, v56
	v_fmac_f32_e32 v72, v243, v55
	v_fmac_f32_e32 v73, v243, v57
	v_fmac_f32_e32 v70, v242, v58
	v_fmac_f32_e32 v71, v242, v60
	v_fmac_f32_e32 v70, v243, v59
	v_fmac_f32_e32 v71, v243, v61
	v_fmac_f32_e32 v68, v242, v62
	v_fmac_f32_e32 v69, v242, v64
	v_fmac_f32_e32 v68, v243, v63
	v_fmac_f32_e32 v69, v243, v65
	v_add_u32_e32 v232, s4, v0
	s_add_i32 s4, s4, 8
	ds_read2st64_b64 v[2:5], v232 offset0:0 offset1:2
	ds_read2st64_b64 v[6:9], v232 offset0:4 offset1:6
	ds_read2st64_b64 v[10:13], v232 offset0:8 offset1:10
	ds_read2st64_b64 v[14:17], v232 offset0:12 offset1:14
	ds_read2st64_b64 v[18:21], v232 offset0:16 offset1:18
	ds_read2st64_b64 v[22:25], v232 offset0:20 offset1:22
	ds_read2st64_b64 v[26:29], v232 offset0:24 offset1:26
	ds_read2st64_b64 v[30:33], v232 offset0:28 offset1:30
	ds_read2st64_b64 v[34:37], v232 offset0:32 offset1:34
	ds_read2st64_b64 v[38:41], v232 offset0:36 offset1:38
	ds_read2st64_b64 v[42:45], v232 offset0:40 offset1:42
	ds_read2st64_b64 v[46:49], v232 offset0:44 offset1:46
	ds_read2st64_b64 v[50:53], v232 offset0:48 offset1:50
	ds_read2st64_b64 v[54:57], v232 offset0:52 offset1:54
	ds_read2st64_b64 v[58:61], v232 offset0:56 offset1:58
	ds_read2st64_b64 v[62:65], v232 offset0:60 offset1:62
	s_waitcnt lgkmcnt(12)
	v_fmac_f32_e32 v100, v244, v2
	v_fmac_f32_e32 v101, v244, v4
	v_fmac_f32_e32 v100, v245, v3
	v_fmac_f32_e32 v101, v245, v5
	v_fmac_f32_e32 v98, v244, v6
	v_fmac_f32_e32 v99, v244, v8
	v_fmac_f32_e32 v98, v245, v7
	v_fmac_f32_e32 v99, v245, v9
	v_fmac_f32_e32 v96, v244, v10
	v_fmac_f32_e32 v97, v244, v12
	v_fmac_f32_e32 v96, v245, v11
	v_fmac_f32_e32 v97, v245, v13
	v_fmac_f32_e32 v94, v244, v14
	v_fmac_f32_e32 v95, v244, v16
	v_fmac_f32_e32 v94, v245, v15
	v_fmac_f32_e32 v95, v245, v17
	s_waitcnt lgkmcnt(8)
	v_fmac_f32_e32 v92, v244, v18
	v_fmac_f32_e32 v93, v244, v20
	v_fmac_f32_e32 v92, v245, v19
	v_fmac_f32_e32 v93, v245, v21
	v_fmac_f32_e32 v88, v244, v22
	v_fmac_f32_e32 v89, v244, v24
	v_fmac_f32_e32 v88, v245, v23
	v_fmac_f32_e32 v89, v245, v25
	v_fmac_f32_e32 v86, v244, v26
	v_fmac_f32_e32 v87, v244, v28
	v_fmac_f32_e32 v86, v245, v27
	v_fmac_f32_e32 v87, v245, v29
	v_fmac_f32_e32 v84, v244, v30
	v_fmac_f32_e32 v85, v244, v32
	v_fmac_f32_e32 v84, v245, v31
	v_fmac_f32_e32 v85, v245, v33
	s_waitcnt lgkmcnt(4)
	v_fmac_f32_e32 v82, v244, v34
	v_fmac_f32_e32 v83, v244, v36
	v_fmac_f32_e32 v82, v245, v35
	v_fmac_f32_e32 v83, v245, v37
	v_fmac_f32_e32 v80, v244, v38
	v_fmac_f32_e32 v81, v244, v40
	v_fmac_f32_e32 v80, v245, v39
	v_fmac_f32_e32 v81, v245, v41
	v_fmac_f32_e32 v78, v244, v42
	v_fmac_f32_e32 v79, v244, v44
	v_fmac_f32_e32 v78, v245, v43
	v_fmac_f32_e32 v79, v245, v45
	v_fmac_f32_e32 v76, v244, v46
	v_fmac_f32_e32 v77, v244, v48
	v_fmac_f32_e32 v76, v245, v47
	v_fmac_f32_e32 v77, v245, v49
	s_waitcnt lgkmcnt(0)
	v_fmac_f32_e32 v74, v244, v50
	v_fmac_f32_e32 v75, v244, v52
	v_fmac_f32_e32 v74, v245, v51
	v_fmac_f32_e32 v75, v245, v53
	v_fmac_f32_e32 v72, v244, v54
	v_fmac_f32_e32 v73, v244, v56
	v_fmac_f32_e32 v72, v245, v55
	v_fmac_f32_e32 v73, v245, v57
	v_fmac_f32_e32 v70, v244, v58
	v_fmac_f32_e32 v71, v244, v60
	v_fmac_f32_e32 v70, v245, v59
	v_fmac_f32_e32 v71, v245, v61
	v_fmac_f32_e32 v68, v244, v62
	v_fmac_f32_e32 v69, v244, v64
	v_fmac_f32_e32 v68, v245, v63
	v_fmac_f32_e32 v69, v245, v65
	v_add_u32_e32 v232, s4, v0
	s_add_i32 s4, s4, 8
	ds_read2st64_b64 v[2:5], v232 offset0:0 offset1:2
	ds_read2st64_b64 v[6:9], v232 offset0:4 offset1:6
	ds_read2st64_b64 v[10:13], v232 offset0:8 offset1:10
	ds_read2st64_b64 v[14:17], v232 offset0:12 offset1:14
	ds_read2st64_b64 v[18:21], v232 offset0:16 offset1:18
	ds_read2st64_b64 v[22:25], v232 offset0:20 offset1:22
	ds_read2st64_b64 v[26:29], v232 offset0:24 offset1:26
	ds_read2st64_b64 v[30:33], v232 offset0:28 offset1:30
	ds_read2st64_b64 v[34:37], v232 offset0:32 offset1:34
	ds_read2st64_b64 v[38:41], v232 offset0:36 offset1:38
	ds_read2st64_b64 v[42:45], v232 offset0:40 offset1:42
	ds_read2st64_b64 v[46:49], v232 offset0:44 offset1:46
	ds_read2st64_b64 v[50:53], v232 offset0:48 offset1:50
	ds_read2st64_b64 v[54:57], v232 offset0:52 offset1:54
	ds_read2st64_b64 v[58:61], v232 offset0:56 offset1:58
	ds_read2st64_b64 v[62:65], v232 offset0:60 offset1:62
	s_waitcnt lgkmcnt(12)
; __device__ __forceinline__ void pool_job(const Params& p, char* smem, int l, int seqrow0, int L, int t0) {
;     ...
;     const int g = tid >> 6, j = tid & 63;
;     const float* pw = p.pool_w + (size_t)(l * 4 + g) * 4096;
;     float acc[32];
; #pragma unroll
;     for (int tt = 0; tt < 32; ++tt) acc[tt] = 0.f;
;     for (int cch = 0; cch < 64; ++cch) {
;       float wv = pw[cch * 64 + j];
; #pragma unroll
;       for (int tt = 0; tt < 32; ++tt) acc[tt] += ds[tt * 256 + g * 64 + cch] * wv;
;     }
	v_fmac_f32_e32 v100, v246, v2
	v_fmac_f32_e32 v101, v246, v4
	v_fmac_f32_e32 v100, v247, v3
	v_fmac_f32_e32 v101, v247, v5
	v_fmac_f32_e32 v98, v246, v6
	v_fmac_f32_e32 v99, v246, v8
	v_fmac_f32_e32 v98, v247, v7
	v_fmac_f32_e32 v99, v247, v9
	v_fmac_f32_e32 v96, v246, v10
	v_fmac_f32_e32 v97, v246, v12
	v_fmac_f32_e32 v96, v247, v11
	v_fmac_f32_e32 v97, v247, v13
	v_fmac_f32_e32 v94, v246, v14
	v_fmac_f32_e32 v95, v246, v16
	v_fmac_f32_e32 v94, v247, v15
	v_fmac_f32_e32 v95, v247, v17
	s_waitcnt lgkmcnt(8)
	v_fmac_f32_e32 v92, v246, v18
	v_fmac_f32_e32 v93, v246, v20
	v_fmac_f32_e32 v92, v247, v19
	v_fmac_f32_e32 v93, v247, v21
	v_fmac_f32_e32 v88, v246, v22
	v_fmac_f32_e32 v89, v246, v24
	v_fmac_f32_e32 v88, v247, v23
	v_fmac_f32_e32 v89, v247, v25
	v_fmac_f32_e32 v86, v246, v26
	v_fmac_f32_e32 v87, v246, v28
	v_fmac_f32_e32 v86, v247, v27
	v_fmac_f32_e32 v87, v247, v29
	v_fmac_f32_e32 v84, v246, v30
	v_fmac_f32_e32 v85, v246, v32
	v_fmac_f32_e32 v84, v247, v31
	v_fmac_f32_e32 v85, v247, v33
	s_waitcnt lgkmcnt(4)
	v_fmac_f32_e32 v82, v246, v34
	v_fmac_f32_e32 v83, v246, v36
	v_fmac_f32_e32 v82, v247, v35
	v_fmac_f32_e32 v83, v247, v37
	v_fmac_f32_e32 v80, v246, v38
	v_fmac_f32_e32 v81, v246, v40
	v_fmac_f32_e32 v80, v247, v39
	v_fmac_f32_e32 v81, v247, v41
	v_fmac_f32_e32 v78, v246, v42
	v_fmac_f32_e32 v79, v246, v44
	v_fmac_f32_e32 v78, v247, v43
	v_fmac_f32_e32 v79, v247, v45
	v_fmac_f32_e32 v76, v246, v46
	v_fmac_f32_e32 v77, v246, v48
	v_fmac_f32_e32 v76, v247, v47
	v_fmac_f32_e32 v77, v247, v49
	s_waitcnt lgkmcnt(0)
	v_fmac_f32_e32 v74, v246, v50
	v_fmac_f32_e32 v75, v246, v52
	v_fmac_f32_e32 v74, v247, v51
	v_fmac_f32_e32 v75, v247, v53
	v_fmac_f32_e32 v72, v246, v54
	v_fmac_f32_e32 v73, v246, v56
	v_fmac_f32_e32 v72, v247, v55
	v_fmac_f32_e32 v73, v247, v57
	v_fmac_f32_e32 v70, v246, v58
	v_fmac_f32_e32 v71, v246, v60
	v_fmac_f32_e32 v70, v247, v59
	v_fmac_f32_e32 v71, v247, v61
	v_fmac_f32_e32 v68, v246, v62
	v_fmac_f32_e32 v69, v246, v64
	v_fmac_f32_e32 v68, v247, v63
	v_fmac_f32_e32 v69, v247, v65
	v_add_u32_e32 v232, s4, v0
	s_add_i32 s4, s4, 8
	ds_read2st64_b64 v[2:5], v232 offset0:0 offset1:2
	ds_read2st64_b64 v[6:9], v232 offset0:4 offset1:6
	ds_read2st64_b64 v[10:13], v232 offset0:8 offset1:10
	ds_read2st64_b64 v[14:17], v232 offset0:12 offset1:14
	ds_read2st64_b64 v[18:21], v232 offset0:16 offset1:18
	ds_read2st64_b64 v[22:25], v232 offset0:20 offset1:22
	ds_read2st64_b64 v[26:29], v232 offset0:24 offset1:26
	ds_read2st64_b64 v[30:33], v232 offset0:28 offset1:30
	ds_read2st64_b64 v[34:37], v232 offset0:32 offset1:34
	ds_read2st64_b64 v[38:41], v232 offset0:36 offset1:38
	ds_read2st64_b64 v[42:45], v232 offset0:40 offset1:42
	ds_read2st64_b64 v[46:49], v232 offset0:44 offset1:46
	ds_read2st64_b64 v[50:53], v232 offset0:48 offset1:50
	ds_read2st64_b64 v[54:57], v232 offset0:52 offset1:54
	ds_read2st64_b64 v[58:61], v232 offset0:56 offset1:58
	ds_read2st64_b64 v[62:65], v232 offset0:60 offset1:62
	s_waitcnt lgkmcnt(12)
	v_fmac_f32_e32 v100, v248, v2
	v_fmac_f32_e32 v101, v248, v4
	v_fmac_f32_e32 v100, v249, v3
	v_fmac_f32_e32 v101, v249, v5
	v_fmac_f32_e32 v98, v248, v6
	v_fmac_f32_e32 v99, v248, v8
	v_fmac_f32_e32 v98, v249, v7
	v_fmac_f32_e32 v99, v249, v9
	v_fmac_f32_e32 v96, v248, v10
	v_fmac_f32_e32 v97, v248, v12
	v_fmac_f32_e32 v96, v249, v11
	v_fmac_f32_e32 v97, v249, v13
	v_fmac_f32_e32 v94, v248, v14
	v_fmac_f32_e32 v95, v248, v16
	v_fmac_f32_e32 v94, v249, v15
	v_fmac_f32_e32 v95, v249, v17
	s_waitcnt lgkmcnt(8)
	v_fmac_f32_e32 v92, v248, v18
	v_fmac_f32_e32 v93, v248, v20
	v_fmac_f32_e32 v92, v249, v19
	v_fmac_f32_e32 v93, v249, v21
	v_fmac_f32_e32 v88, v248, v22
	v_fmac_f32_e32 v89, v248, v24
	v_fmac_f32_e32 v88, v249, v23
	v_fmac_f32_e32 v89, v249, v25
	v_fmac_f32_e32 v86, v248, v26
	v_fmac_f32_e32 v87, v248, v28
	v_fmac_f32_e32 v86, v249, v27
	v_fmac_f32_e32 v87, v249, v29
	v_fmac_f32_e32 v84, v248, v30
	v_fmac_f32_e32 v85, v248, v32
	v_fmac_f32_e32 v84, v249, v31
	v_fmac_f32_e32 v85, v249, v33
	s_waitcnt lgkmcnt(4)
	v_fmac_f32_e32 v82, v248, v34
	v_fmac_f32_e32 v83, v248, v36
	v_fmac_f32_e32 v82, v249, v35
	v_fmac_f32_e32 v83, v249, v37
	v_fmac_f32_e32 v80, v248, v38
	v_fmac_f32_e32 v81, v248, v40
	v_fmac_f32_e32 v80, v249, v39
	v_fmac_f32_e32 v81, v249, v41
	v_fmac_f32_e32 v78, v248, v42
	v_fmac_f32_e32 v79, v248, v44
	v_fmac_f32_e32 v78, v249, v43
	v_fmac_f32_e32 v79, v249, v45
	v_fmac_f32_e32 v76, v248, v46
	v_fmac_f32_e32 v77, v248, v48
	v_fmac_f32_e32 v76, v249, v47
	v_fmac_f32_e32 v77, v249, v49
	s_waitcnt lgkmcnt(0)
	v_fmac_f32_e32 v74, v248, v50
	v_fmac_f32_e32 v75, v248, v52
	v_fmac_f32_e32 v74, v249, v51
	v_fmac_f32_e32 v75, v249, v53
	v_fmac_f32_e32 v72, v248, v54
	v_fmac_f32_e32 v73, v248, v56
	v_fmac_f32_e32 v72, v249, v55
	v_fmac_f32_e32 v73, v249, v57
	v_fmac_f32_e32 v70, v248, v58
	v_fmac_f32_e32 v71, v248, v60
	v_fmac_f32_e32 v70, v249, v59
	v_fmac_f32_e32 v71, v249, v61
	v_fmac_f32_e32 v68, v248, v62
	v_fmac_f32_e32 v69, v248, v64
	v_fmac_f32_e32 v68, v249, v63
	v_fmac_f32_e32 v69, v249, v65
	v_add_u32_e32 v232, s4, v0
	s_add_i32 s4, s4, 8
	ds_read2st64_b64 v[2:5], v232 offset0:0 offset1:2
	ds_read2st64_b64 v[6:9], v232 offset0:4 offset1:6
	ds_read2st64_b64 v[10:13], v232 offset0:8 offset1:10
	ds_read2st64_b64 v[14:17], v232 offset0:12 offset1:14
	ds_read2st64_b64 v[18:21], v232 offset0:16 offset1:18
	ds_read2st64_b64 v[22:25], v232 offset0:20 offset1:22
	ds_read2st64_b64 v[26:29], v232 offset0:24 offset1:26
	ds_read2st64_b64 v[30:33], v232 offset0:28 offset1:30
	ds_read2st64_b64 v[34:37], v232 offset0:32 offset1:34
	ds_read2st64_b64 v[38:41], v232 offset0:36 offset1:38
	ds_read2st64_b64 v[42:45], v232 offset0:40 offset1:42
	ds_read2st64_b64 v[46:49], v232 offset0:44 offset1:46
	ds_read2st64_b64 v[50:53], v232 offset0:48 offset1:50
	ds_read2st64_b64 v[54:57], v232 offset0:52 offset1:54
	ds_read2st64_b64 v[58:61], v232 offset0:56 offset1:58
	ds_read2st64_b64 v[62:65], v232 offset0:60 offset1:62
	s_waitcnt lgkmcnt(12)
; __device__ __forceinline__ void pool_job(const Params& p, char* smem, int l, int seqrow0, int L, int t0) {
;     ...
;     const int g = tid >> 6, j = tid & 63;
;     const float* pw = p.pool_w + (size_t)(l * 4 + g) * 4096;
;     float acc[32];
; #pragma unroll
;     for (int tt = 0; tt < 32; ++tt) acc[tt] = 0.f;
;     for (int cch = 0; cch < 64; ++cch) {
;       float wv = pw[cch * 64 + j];
; #pragma unroll
;       for (int tt = 0; tt < 32; ++tt) acc[tt] += ds[tt * 256 + g * 64 + cch] * wv;
;     }
	v_fmac_f32_e32 v100, v250, v2
	v_fmac_f32_e32 v101, v250, v4
	v_fmac_f32_e32 v100, v251, v3
	v_fmac_f32_e32 v101, v251, v5
	v_fmac_f32_e32 v98, v250, v6
	v_fmac_f32_e32 v99, v250, v8
	v_fmac_f32_e32 v98, v251, v7
	v_fmac_f32_e32 v99, v251, v9
	v_fmac_f32_e32 v96, v250, v10
	v_fmac_f32_e32 v97, v250, v12
	v_fmac_f32_e32 v96, v251, v11
	v_fmac_f32_e32 v97, v251, v13
	v_fmac_f32_e32 v94, v250, v14
	v_fmac_f32_e32 v95, v250, v16
	v_fmac_f32_e32 v94, v251, v15
	v_fmac_f32_e32 v95, v251, v17
	s_waitcnt lgkmcnt(8)
	v_fmac_f32_e32 v92, v250, v18
	v_fmac_f32_e32 v93, v250, v20
	v_fmac_f32_e32 v92, v251, v19
	v_fmac_f32_e32 v93, v251, v21
	v_fmac_f32_e32 v88, v250, v22
	v_fmac_f32_e32 v89, v250, v24
	v_fmac_f32_e32 v88, v251, v23
	v_fmac_f32_e32 v89, v251, v25
	v_fmac_f32_e32 v86, v250, v26
	v_fmac_f32_e32 v87, v250, v28
	v_fmac_f32_e32 v86, v251, v27
	v_fmac_f32_e32 v87, v251, v29
	v_fmac_f32_e32 v84, v250, v30
	v_fmac_f32_e32 v85, v250, v32
	v_fmac_f32_e32 v84, v251, v31
	v_fmac_f32_e32 v85, v251, v33
	s_waitcnt lgkmcnt(4)
	v_fmac_f32_e32 v82, v250, v34
	v_fmac_f32_e32 v83, v250, v36
	v_fmac_f32_e32 v82, v251, v35
	v_fmac_f32_e32 v83, v251, v37
	v_fmac_f32_e32 v80, v250, v38
	v_fmac_f32_e32 v81, v250, v40
	v_fmac_f32_e32 v80, v251, v39
	v_fmac_f32_e32 v81, v251, v41
	v_fmac_f32_e32 v78, v250, v42
	v_fmac_f32_e32 v79, v250, v44
	v_fmac_f32_e32 v78, v251, v43
	v_fmac_f32_e32 v79, v251, v45
	v_fmac_f32_e32 v76, v250, v46
	v_fmac_f32_e32 v77, v250, v48
	v_fmac_f32_e32 v76, v251, v47
	v_fmac_f32_e32 v77, v251, v49
	s_waitcnt lgkmcnt(0)
	v_fmac_f32_e32 v74, v250, v50
	v_fmac_f32_e32 v75, v250, v52
	v_fmac_f32_e32 v74, v251, v51
	v_fmac_f32_e32 v75, v251, v53
	v_fmac_f32_e32 v72, v250, v54
	v_fmac_f32_e32 v73, v250, v56
	v_fmac_f32_e32 v72, v251, v55
	v_fmac_f32_e32 v73, v251, v57
	v_fmac_f32_e32 v70, v250, v58
	v_fmac_f32_e32 v71, v250, v60
	v_fmac_f32_e32 v70, v251, v59
	v_fmac_f32_e32 v71, v251, v61
	v_fmac_f32_e32 v68, v250, v62
	v_fmac_f32_e32 v69, v250, v64
	v_fmac_f32_e32 v68, v251, v63
	v_fmac_f32_e32 v69, v251, v65
	v_add_u32_e32 v232, s4, v0
	s_add_i32 s4, s4, 8
	ds_read2st64_b64 v[2:5], v232 offset0:0 offset1:2
	ds_read2st64_b64 v[6:9], v232 offset0:4 offset1:6
	ds_read2st64_b64 v[10:13], v232 offset0:8 offset1:10
	ds_read2st64_b64 v[14:17], v232 offset0:12 offset1:14
	ds_read2st64_b64 v[18:21], v232 offset0:16 offset1:18
	ds_read2st64_b64 v[22:25], v232 offset0:20 offset1:22
	ds_read2st64_b64 v[26:29], v232 offset0:24 offset1:26
	ds_read2st64_b64 v[30:33], v232 offset0:28 offset1:30
	ds_read2st64_b64 v[34:37], v232 offset0:32 offset1:34
	ds_read2st64_b64 v[38:41], v232 offset0:36 offset1:38
	ds_read2st64_b64 v[42:45], v232 offset0:40 offset1:42
	ds_read2st64_b64 v[46:49], v232 offset0:44 offset1:46
	ds_read2st64_b64 v[50:53], v232 offset0:48 offset1:50
	ds_read2st64_b64 v[54:57], v232 offset0:52 offset1:54
	ds_read2st64_b64 v[58:61], v232 offset0:56 offset1:58
	ds_read2st64_b64 v[62:65], v232 offset0:60 offset1:62
	s_waitcnt lgkmcnt(12)
	v_fmac_f32_e32 v100, v252, v2
	v_fmac_f32_e32 v101, v252, v4
	v_fmac_f32_e32 v100, v253, v3
	v_fmac_f32_e32 v101, v253, v5
	v_fmac_f32_e32 v98, v252, v6
	v_fmac_f32_e32 v99, v252, v8
	v_fmac_f32_e32 v98, v253, v7
	v_fmac_f32_e32 v99, v253, v9
	v_fmac_f32_e32 v96, v252, v10
	v_fmac_f32_e32 v97, v252, v12
	v_fmac_f32_e32 v96, v253, v11
	v_fmac_f32_e32 v97, v253, v13
	v_fmac_f32_e32 v94, v252, v14
	v_fmac_f32_e32 v95, v252, v16
	v_fmac_f32_e32 v94, v253, v15
	v_fmac_f32_e32 v95, v253, v17
	s_waitcnt lgkmcnt(8)
	v_fmac_f32_e32 v92, v252, v18
	v_fmac_f32_e32 v93, v252, v20
	v_fmac_f32_e32 v92, v253, v19
	v_fmac_f32_e32 v93, v253, v21
	v_fmac_f32_e32 v88, v252, v22
	v_fmac_f32_e32 v89, v252, v24
	v_fmac_f32_e32 v88, v253, v23
	v_fmac_f32_e32 v89, v253, v25
	v_fmac_f32_e32 v86, v252, v26
	v_fmac_f32_e32 v87, v252, v28
	v_fmac_f32_e32 v86, v253, v27
	v_fmac_f32_e32 v87, v253, v29
	v_fmac_f32_e32 v84, v252, v30
	v_fmac_f32_e32 v85, v252, v32
	v_fmac_f32_e32 v84, v253, v31
	v_fmac_f32_e32 v85, v253, v33
	s_waitcnt lgkmcnt(4)
	v_fmac_f32_e32 v82, v252, v34
	v_fmac_f32_e32 v83, v252, v36
	v_fmac_f32_e32 v82, v253, v35
	v_fmac_f32_e32 v83, v253, v37
	v_fmac_f32_e32 v80, v252, v38
	v_fmac_f32_e32 v81, v252, v40
	v_fmac_f32_e32 v80, v253, v39
	v_fmac_f32_e32 v81, v253, v41
	v_fmac_f32_e32 v78, v252, v42
	v_fmac_f32_e32 v79, v252, v44
	v_fmac_f32_e32 v78, v253, v43
	v_fmac_f32_e32 v79, v253, v45
	v_fmac_f32_e32 v76, v252, v46
	v_fmac_f32_e32 v77, v252, v48
	v_fmac_f32_e32 v76, v253, v47
	v_fmac_f32_e32 v77, v253, v49
	s_waitcnt lgkmcnt(0)
	v_fmac_f32_e32 v74, v252, v50
	v_fmac_f32_e32 v75, v252, v52
	v_fmac_f32_e32 v74, v253, v51
	v_fmac_f32_e32 v75, v253, v53
	v_fmac_f32_e32 v72, v252, v54
	v_fmac_f32_e32 v73, v252, v56
	v_fmac_f32_e32 v72, v253, v55
	v_fmac_f32_e32 v73, v253, v57
	v_fmac_f32_e32 v70, v252, v58
	v_fmac_f32_e32 v71, v252, v60
	v_fmac_f32_e32 v70, v253, v59
	v_fmac_f32_e32 v71, v253, v61
	v_fmac_f32_e32 v68, v252, v62
	v_fmac_f32_e32 v69, v252, v64
	v_fmac_f32_e32 v68, v253, v63
	v_fmac_f32_e32 v69, v253, v65
	v_add_u32_e32 v232, s4, v0
	s_add_i32 s4, s4, 8
	ds_read2st64_b64 v[2:5], v232 offset0:0 offset1:2
	ds_read2st64_b64 v[6:9], v232 offset0:4 offset1:6
	ds_read2st64_b64 v[10:13], v232 offset0:8 offset1:10
	ds_read2st64_b64 v[14:17], v232 offset0:12 offset1:14
	ds_read2st64_b64 v[18:21], v232 offset0:16 offset1:18
	ds_read2st64_b64 v[22:25], v232 offset0:20 offset1:22
	ds_read2st64_b64 v[26:29], v232 offset0:24 offset1:26
	ds_read2st64_b64 v[30:33], v232 offset0:28 offset1:30
	ds_read2st64_b64 v[34:37], v232 offset0:32 offset1:34
	ds_read2st64_b64 v[38:41], v232 offset0:36 offset1:38
	ds_read2st64_b64 v[42:45], v232 offset0:40 offset1:42
	ds_read2st64_b64 v[46:49], v232 offset0:44 offset1:46
	ds_read2st64_b64 v[50:53], v232 offset0:48 offset1:50
	ds_read2st64_b64 v[54:57], v232 offset0:52 offset1:54
	ds_read2st64_b64 v[58:61], v232 offset0:56 offset1:58
	ds_read2st64_b64 v[62:65], v232 offset0:60 offset1:62
	s_waitcnt lgkmcnt(12)
; __device__ __forceinline__ void pool_job(const Params& p, char* smem, int l, int seqrow0, int L, int t0) {
;     ...
;     const int g = tid >> 6, j = tid & 63;
;     const float* pw = p.pool_w + (size_t)(l * 4 + g) * 4096;
;     float acc[32];
; #pragma unroll
;     for (int tt = 0; tt < 32; ++tt) acc[tt] = 0.f;
;     for (int cch = 0; cch < 64; ++cch) {
;       float wv = pw[cch * 64 + j];
; #pragma unroll
;       for (int tt = 0; tt < 32; ++tt) acc[tt] += ds[tt * 256 + g * 64 + cch] * wv;
;     }
;     float sc = p.pool_scale[l * 256 + tid];
; #pragma unroll
;     for (int tt = 0; tt < 32; ++tt) MIX[(size_t)(seqrow0 + t0 + tt) * 1024 + 768 + tid] = f2bf(acc[tt] * sc);
	v_fmac_f32_e32 v100, v254, v2
	v_fmac_f32_e32 v101, v254, v4
	v_fmac_f32_e32 v100, v255, v3
	v_fmac_f32_e32 v101, v255, v5
	v_fmac_f32_e32 v98, v254, v6
	v_fmac_f32_e32 v99, v254, v8
	v_fmac_f32_e32 v98, v255, v7
	v_fmac_f32_e32 v99, v255, v9
	v_fmac_f32_e32 v96, v254, v10
	v_fmac_f32_e32 v97, v254, v12
	v_fmac_f32_e32 v96, v255, v11
	v_fmac_f32_e32 v97, v255, v13
	v_fmac_f32_e32 v94, v254, v14
	v_fmac_f32_e32 v95, v254, v16
	v_fmac_f32_e32 v94, v255, v15
	v_fmac_f32_e32 v95, v255, v17
	s_waitcnt lgkmcnt(8)
	v_fmac_f32_e32 v92, v254, v18
	v_fmac_f32_e32 v93, v254, v20
	v_fmac_f32_e32 v92, v255, v19
	v_fmac_f32_e32 v93, v255, v21
	v_fmac_f32_e32 v88, v254, v22
	v_fmac_f32_e32 v89, v254, v24
	v_fmac_f32_e32 v88, v255, v23
	v_fmac_f32_e32 v89, v255, v25
	v_fmac_f32_e32 v86, v254, v26
	v_fmac_f32_e32 v87, v254, v28
	v_fmac_f32_e32 v86, v255, v27
	v_fmac_f32_e32 v87, v255, v29
	v_fmac_f32_e32 v84, v254, v30
	v_fmac_f32_e32 v85, v254, v32
	v_fmac_f32_e32 v84, v255, v31
	v_fmac_f32_e32 v85, v255, v33
	s_waitcnt lgkmcnt(4)
	v_fmac_f32_e32 v82, v254, v34
	v_fmac_f32_e32 v83, v254, v36
	v_fmac_f32_e32 v82, v255, v35
	v_fmac_f32_e32 v83, v255, v37
	v_fmac_f32_e32 v80, v254, v38
	v_fmac_f32_e32 v81, v254, v40
	v_fmac_f32_e32 v80, v255, v39
	v_fmac_f32_e32 v81, v255, v41
	v_fmac_f32_e32 v78, v254, v42
	v_fmac_f32_e32 v79, v254, v44
	v_fmac_f32_e32 v78, v255, v43
	v_fmac_f32_e32 v79, v255, v45
	v_fmac_f32_e32 v76, v254, v46
	v_fmac_f32_e32 v77, v254, v48
	v_fmac_f32_e32 v76, v255, v47
	v_fmac_f32_e32 v77, v255, v49
	s_waitcnt lgkmcnt(0)
	v_fmac_f32_e32 v74, v254, v50
	v_fmac_f32_e32 v75, v254, v52
	v_fmac_f32_e32 v74, v255, v51
	v_fmac_f32_e32 v75, v255, v53
	v_fmac_f32_e32 v72, v254, v54
	v_fmac_f32_e32 v73, v254, v56
	v_fmac_f32_e32 v72, v255, v55
	v_fmac_f32_e32 v73, v255, v57
	v_fmac_f32_e32 v70, v254, v58
	v_fmac_f32_e32 v71, v254, v60
	v_fmac_f32_e32 v70, v255, v59
	v_fmac_f32_e32 v71, v255, v61
	v_fmac_f32_e32 v68, v254, v62
	v_fmac_f32_e32 v69, v254, v64
	v_fmac_f32_e32 v68, v255, v63
	v_fmac_f32_e32 v69, v255, v65
	v_lshl_add_u32 v2, s18, 8, v66
	v_readlane_b32 s60, v239, 39
	v_ashrrev_i32_e32 v3, 31, v2
	v_readlane_b32 s74, v239, 53
	v_readlane_b32 s75, v239, 54
	v_ashrrev_i32_e32 v67, 31, v66
	s_add_i32 s2, s2, s17
	v_lshl_add_u64 v[2:3], v[2:3], 2, s[74:75]
	global_load_dword v0, v[2:3], off
	v_lshl_add_u64 v[2:3], v[66:67], 1, s[0:1]
	s_mov_b64 s[0:1], 0x28096700
	v_lshl_add_u64 v[2:3], v[2:3], 0, s[0:1]
	s_lshl_b64 s[0:1], s[2:3], 11
	v_readlane_b32 s61, v239, 40
	v_readlane_b32 s62, v239, 41
	v_readlane_b32 s63, v239, 42
	v_readlane_b32 s64, v239, 43
	v_readlane_b32 s65, v239, 44
	v_readlane_b32 s66, v239, 45
	v_readlane_b32 s67, v239, 46
	v_readlane_b32 s68, v239, 47
	v_readlane_b32 s69, v239, 48
	v_readlane_b32 s70, v239, 49
	v_readlane_b32 s71, v239, 50
	v_readlane_b32 s72, v239, 51
	v_readlane_b32 s73, v239, 52
	s_mov_b64 s[12:13], -1
	s_waitcnt vmcnt(0)
	v_mul_f32_e32 v4, v100, v0
	v_bfe_u32 v5, v4, 16, 1
	v_add3_u32 v6, v4, v5, s33
	v_lshl_add_u64 v[4:5], v[2:3], 0, s[0:1]
	global_store_short_d16_hi v[4:5], v6, off
	v_mul_f32_e32 v4, v101, v0
	s_or_b32 s0, s2, 1
	s_mov_b32 s1, s3
	v_bfe_u32 v5, v4, 16, 1
	s_lshl_b64 s[0:1], s[0:1], 11
	v_add3_u32 v6, v4, v5, s33
	v_lshl_add_u64 v[4:5], v[2:3], 0, s[0:1]
	global_store_short_d16_hi v[4:5], v6, off
	v_mul_f32_e32 v4, v98, v0
	s_or_b32 s0, s2, 2
	s_mov_b32 s1, s3
	v_bfe_u32 v5, v4, 16, 1
	s_lshl_b64 s[0:1], s[0:1], 11
	v_add3_u32 v6, v4, v5, s33
	v_lshl_add_u64 v[4:5], v[2:3], 0, s[0:1]
	global_store_short_d16_hi v[4:5], v6, off
	v_mul_f32_e32 v4, v99, v0
	s_or_b32 s0, s2, 3
	s_mov_b32 s1, s3
	v_bfe_u32 v5, v4, 16, 1
	s_lshl_b64 s[0:1], s[0:1], 11
	v_add3_u32 v6, v4, v5, s33
	v_lshl_add_u64 v[4:5], v[2:3], 0, s[0:1]
	global_store_short_d16_hi v[4:5], v6, off
	v_mul_f32_e32 v4, v96, v0
	s_or_b32 s0, s2, 4
	s_mov_b32 s1, s3
	v_bfe_u32 v5, v4, 16, 1
	s_lshl_b64 s[0:1], s[0:1], 11
	v_add3_u32 v6, v4, v5, s33
	v_lshl_add_u64 v[4:5], v[2:3], 0, s[0:1]
	global_store_short_d16_hi v[4:5], v6, off
	v_mul_f32_e32 v4, v97, v0
	s_or_b32 s0, s2, 5
	s_mov_b32 s1, s3
	v_bfe_u32 v5, v4, 16, 1
	s_lshl_b64 s[0:1], s[0:1], 11
	v_add3_u32 v6, v4, v5, s33
	v_lshl_add_u64 v[4:5], v[2:3], 0, s[0:1]
	global_store_short_d16_hi v[4:5], v6, off
	v_mul_f32_e32 v4, v94, v0
	s_or_b32 s0, s2, 6
	s_mov_b32 s1, s3
	v_bfe_u32 v5, v4, 16, 1
	s_lshl_b64 s[0:1], s[0:1], 11
	v_add3_u32 v6, v4, v5, s33
	v_lshl_add_u64 v[4:5], v[2:3], 0, s[0:1]
	global_store_short_d16_hi v[4:5], v6, off
	v_mul_f32_e32 v4, v95, v0
	s_or_b32 s0, s2, 7
	s_mov_b32 s1, s3
	v_bfe_u32 v5, v4, 16, 1
	s_lshl_b64 s[0:1], s[0:1], 11
	v_add3_u32 v6, v4, v5, s33
	v_lshl_add_u64 v[4:5], v[2:3], 0, s[0:1]
	global_store_short_d16_hi v[4:5], v6, off
	v_mul_f32_e32 v4, v92, v0
	s_or_b32 s0, s2, 8
	s_mov_b32 s1, s3
	v_bfe_u32 v5, v4, 16, 1
	s_lshl_b64 s[0:1], s[0:1], 11
	v_add3_u32 v6, v4, v5, s33
	v_lshl_add_u64 v[4:5], v[2:3], 0, s[0:1]
	global_store_short_d16_hi v[4:5], v6, off
	v_mul_f32_e32 v4, v93, v0
	s_or_b32 s0, s2, 9
	s_mov_b32 s1, s3
	v_bfe_u32 v5, v4, 16, 1
	s_lshl_b64 s[0:1], s[0:1], 11
	v_add3_u32 v6, v4, v5, s33
	v_lshl_add_u64 v[4:5], v[2:3], 0, s[0:1]
	global_store_short_d16_hi v[4:5], v6, off
; __device__ __forceinline__ void pool_job(const Params& p, char* smem, int l, int seqrow0, int L, int t0) {
;     ...
;     float sc = p.pool_scale[l * 256 + tid];
; #pragma unroll
;     for (int tt = 0; tt < 32; ++tt) MIX[(size_t)(seqrow0 + t0 + tt) * 1024 + 768 + tid] = f2bf(acc[tt] * sc);
;   }
;   __syncthreads();
	v_mul_f32_e32 v4, v88, v0
	s_or_b32 s0, s2, 10
	s_mov_b32 s1, s3
	v_bfe_u32 v5, v4, 16, 1
	s_lshl_b64 s[0:1], s[0:1], 11
	v_add3_u32 v6, v4, v5, s33
	v_lshl_add_u64 v[4:5], v[2:3], 0, s[0:1]
	global_store_short_d16_hi v[4:5], v6, off
	v_mul_f32_e32 v4, v89, v0
	s_or_b32 s0, s2, 11
	s_mov_b32 s1, s3
	v_bfe_u32 v5, v4, 16, 1
	s_lshl_b64 s[0:1], s[0:1], 11
	v_add3_u32 v6, v4, v5, s33
	v_lshl_add_u64 v[4:5], v[2:3], 0, s[0:1]
	global_store_short_d16_hi v[4:5], v6, off
	v_mul_f32_e32 v4, v86, v0
	s_or_b32 s0, s2, 12
	s_mov_b32 s1, s3
	v_bfe_u32 v5, v4, 16, 1
	s_lshl_b64 s[0:1], s[0:1], 11
	v_add3_u32 v6, v4, v5, s33
	v_lshl_add_u64 v[4:5], v[2:3], 0, s[0:1]
	global_store_short_d16_hi v[4:5], v6, off
	v_mul_f32_e32 v4, v87, v0
	s_or_b32 s0, s2, 13
	s_mov_b32 s1, s3
	v_bfe_u32 v5, v4, 16, 1
	s_lshl_b64 s[0:1], s[0:1], 11
	v_add3_u32 v6, v4, v5, s33
	v_lshl_add_u64 v[4:5], v[2:3], 0, s[0:1]
	global_store_short_d16_hi v[4:5], v6, off
	v_mul_f32_e32 v4, v84, v0
	s_or_b32 s0, s2, 14
	s_mov_b32 s1, s3
	v_bfe_u32 v5, v4, 16, 1
	s_lshl_b64 s[0:1], s[0:1], 11
	v_add3_u32 v6, v4, v5, s33
	v_lshl_add_u64 v[4:5], v[2:3], 0, s[0:1]
	global_store_short_d16_hi v[4:5], v6, off
	v_mul_f32_e32 v4, v85, v0
	s_or_b32 s0, s2, 15
	s_mov_b32 s1, s3
	v_bfe_u32 v5, v4, 16, 1
	s_lshl_b64 s[0:1], s[0:1], 11
	v_add3_u32 v6, v4, v5, s33
	v_lshl_add_u64 v[4:5], v[2:3], 0, s[0:1]
	global_store_short_d16_hi v[4:5], v6, off
	v_mul_f32_e32 v4, v82, v0
	s_or_b32 s0, s2, 16
	s_mov_b32 s1, s3
	v_bfe_u32 v5, v4, 16, 1
	s_lshl_b64 s[0:1], s[0:1], 11
	v_add3_u32 v6, v4, v5, s33
	v_lshl_add_u64 v[4:5], v[2:3], 0, s[0:1]
	global_store_short_d16_hi v[4:5], v6, off
	v_mul_f32_e32 v4, v83, v0
	s_or_b32 s0, s2, 17
	s_mov_b32 s1, s3
	v_bfe_u32 v5, v4, 16, 1
	s_lshl_b64 s[0:1], s[0:1], 11
	v_add3_u32 v6, v4, v5, s33
	v_lshl_add_u64 v[4:5], v[2:3], 0, s[0:1]
	global_store_short_d16_hi v[4:5], v6, off
	v_mul_f32_e32 v4, v80, v0
	s_or_b32 s0, s2, 18
	s_mov_b32 s1, s3
	v_bfe_u32 v5, v4, 16, 1
	s_lshl_b64 s[0:1], s[0:1], 11
	v_add3_u32 v6, v4, v5, s33
	v_lshl_add_u64 v[4:5], v[2:3], 0, s[0:1]
	global_store_short_d16_hi v[4:5], v6, off
	v_mul_f32_e32 v4, v81, v0
	s_or_b32 s0, s2, 19
	s_mov_b32 s1, s3
	v_bfe_u32 v5, v4, 16, 1
	s_lshl_b64 s[0:1], s[0:1], 11
	v_add3_u32 v6, v4, v5, s33
	v_lshl_add_u64 v[4:5], v[2:3], 0, s[0:1]
	global_store_short_d16_hi v[4:5], v6, off
	v_mul_f32_e32 v4, v78, v0
	s_or_b32 s0, s2, 20
	s_mov_b32 s1, s3
	v_bfe_u32 v5, v4, 16, 1
	s_lshl_b64 s[0:1], s[0:1], 11
	v_add3_u32 v6, v4, v5, s33
	v_lshl_add_u64 v[4:5], v[2:3], 0, s[0:1]
	global_store_short_d16_hi v[4:5], v6, off
	v_mul_f32_e32 v4, v79, v0
	s_or_b32 s0, s2, 21
	s_mov_b32 s1, s3
	v_bfe_u32 v5, v4, 16, 1
	s_lshl_b64 s[0:1], s[0:1], 11
	v_add3_u32 v6, v4, v5, s33
	v_lshl_add_u64 v[4:5], v[2:3], 0, s[0:1]
	global_store_short_d16_hi v[4:5], v6, off
	v_mul_f32_e32 v4, v76, v0
	s_or_b32 s0, s2, 22
	s_mov_b32 s1, s3
	v_bfe_u32 v5, v4, 16, 1
	s_lshl_b64 s[0:1], s[0:1], 11
	v_add3_u32 v6, v4, v5, s33
	v_lshl_add_u64 v[4:5], v[2:3], 0, s[0:1]
	global_store_short_d16_hi v[4:5], v6, off
	v_mul_f32_e32 v4, v77, v0
	s_or_b32 s0, s2, 23
	s_mov_b32 s1, s3
	v_bfe_u32 v5, v4, 16, 1
	s_lshl_b64 s[0:1], s[0:1], 11
	v_add3_u32 v6, v4, v5, s33
	v_lshl_add_u64 v[4:5], v[2:3], 0, s[0:1]
	global_store_short_d16_hi v[4:5], v6, off
	v_mul_f32_e32 v4, v74, v0
	s_or_b32 s0, s2, 24
	s_mov_b32 s1, s3
	v_bfe_u32 v5, v4, 16, 1
	s_lshl_b64 s[0:1], s[0:1], 11
	v_add3_u32 v6, v4, v5, s33
	v_lshl_add_u64 v[4:5], v[2:3], 0, s[0:1]
	global_store_short_d16_hi v[4:5], v6, off
	v_mul_f32_e32 v4, v75, v0
	s_or_b32 s0, s2, 25
	s_mov_b32 s1, s3
	v_bfe_u32 v5, v4, 16, 1
	s_lshl_b64 s[0:1], s[0:1], 11
	v_add3_u32 v6, v4, v5, s33
	v_lshl_add_u64 v[4:5], v[2:3], 0, s[0:1]
	global_store_short_d16_hi v[4:5], v6, off
	v_mul_f32_e32 v4, v72, v0
	s_or_b32 s0, s2, 26
	s_mov_b32 s1, s3
	v_bfe_u32 v5, v4, 16, 1
	s_lshl_b64 s[0:1], s[0:1], 11
	v_add3_u32 v6, v4, v5, s33
	v_lshl_add_u64 v[4:5], v[2:3], 0, s[0:1]
	global_store_short_d16_hi v[4:5], v6, off
	v_mul_f32_e32 v4, v73, v0
	s_or_b32 s0, s2, 27
	s_mov_b32 s1, s3
	v_bfe_u32 v5, v4, 16, 1
	s_lshl_b64 s[0:1], s[0:1], 11
	v_add3_u32 v6, v4, v5, s33
	v_lshl_add_u64 v[4:5], v[2:3], 0, s[0:1]
	global_store_short_d16_hi v[4:5], v6, off
	v_mul_f32_e32 v4, v70, v0
	s_or_b32 s0, s2, 28
	s_mov_b32 s1, s3
	v_bfe_u32 v5, v4, 16, 1
	s_lshl_b64 s[0:1], s[0:1], 11
	v_add3_u32 v6, v4, v5, s33
	v_lshl_add_u64 v[4:5], v[2:3], 0, s[0:1]
	global_store_short_d16_hi v[4:5], v6, off
	v_mul_f32_e32 v4, v71, v0
	s_or_b32 s0, s2, 29
	s_mov_b32 s1, s3
	v_bfe_u32 v5, v4, 16, 1
	s_lshl_b64 s[0:1], s[0:1], 11
	v_add3_u32 v6, v4, v5, s33
	v_lshl_add_u64 v[4:5], v[2:3], 0, s[0:1]
	global_store_short_d16_hi v[4:5], v6, off
	v_mul_f32_e32 v4, v68, v0
	s_or_b32 s0, s2, 30
	s_mov_b32 s1, s3
	v_bfe_u32 v5, v4, 16, 1
	s_lshl_b64 s[0:1], s[0:1], 11
	v_add3_u32 v6, v4, v5, s33
	v_lshl_add_u64 v[4:5], v[2:3], 0, s[0:1]
	v_mul_f32_e32 v0, v69, v0
	s_or_b32 s2, s2, 31
	global_store_short_d16_hi v[4:5], v6, off
	v_bfe_u32 v4, v0, 16, 1
	s_lshl_b64 s[0:1], s[2:3], 11
	v_add3_u32 v0, v0, v4, s33
	v_lshl_add_u64 v[2:3], v[2:3], 0, s[0:1]
	global_store_short_d16_hi v[2:3], v0, off
	s_waitcnt lgkmcnt(0)
	s_barrier
	s_branch .LBB0_872
